# EPI_Q rope/store pass rewritten with 8-column groups and 16-byte stores; EPI_Q/EPI_KV row-rms pass batched (16 row loads in flight, pipelined butterflies)
# speedup vs baseline: 1.2218x; 1.0140x over previous
; DEV float lo2f(u32 w) { return __uint_as_float(w << 16); }
; DEV float hi2f(u32 w) { return __uint_as_float(w & 0xffff0000u); }
; template <int HOOK>
; __device__ __forceinline__ void gemm_tile(const u16* __restrict__ A, int lda, const u16* __restrict__ B, int ldb, int K, char* smem, const float* ssq = nullptr) {
;     ...
;   __syncthreads();
;   float* sC = (float*)smem;
; #pragma unroll
;   for (int i = 0; i < 4; i++)
; #pragma unroll
;     for (int j = 0; j < 4; j++)
; #pragma unroll
;       for (int r = 0; r < 4; r++) sC[(wm + i * 16 + lq * 4 + r) * 128 + wn + j * 16 + lr] = acc[i][j][r];
;   __syncthreads();
;     ...
;       for (int i = tid; i < 128 * 32; i += NTHR) {
;         int r = i >> 5, sub = i & 31, c4 = sub * 4;
;         int row = m0 + r;
;         float ss = 0.f;
;         if (EPI == EPI_Q) {
;           uint4 w = *(const uint4*)(Pm + (size_t)row * LDP + sub * 8);
;           float a;
;           a = lo2f(w.x); ss += a * a; a = hi2f(w.x); ss += a * a; a = lo2f(w.y); ss += a * a; a = hi2f(w.y); ss += a * a;
;           a = lo2f(w.z); ss += a * a; a = hi2f(w.z); ss += a * a; a = lo2f(w.w); ss += a * a; a = hi2f(w.w); ss += a * a;
;         } else {
;           uint2 w = *(const uint2*)(Pm + (size_t)row * LDP + 256 + sub * 4);
;           float a;
;           a = lo2f(w.x); ss += a * a; a = hi2f(w.x); ss += a * a; a = lo2f(w.y); ss += a * a; a = hi2f(w.y); ss += a * a;
;         }
;         ss += __shfl_xor(ss, 1, 64); ss += __shfl_xor(ss, 2, 64); ss += __shfl_xor(ss, 4, 64);
;         ss += __shfl_xor(ss, 8, 64); ss += __shfl_xor(ss, 16, 64);
.LBB0_1379:
	s_waitcnt vmcnt(7)
	v_lshlrev_b32_e32 v1, 9, v131
	v_and_or_b32 v0, v127, 64, v129
	v_lshl_or_b32 v1, v135, 11, v1
	v_lshl_or_b32 v0, v0, 2, v1
	v_add_u32_e32 v1, 0x400, v0
	s_barrier
	ds_write2_b32 v0, v92, v88 offset1:16
	ds_write2_b32 v0, v93, v89 offset0:128 offset1:144
	ds_write2_b32 v1, v94, v90 offset1:16
	ds_write2_b32 v1, v95, v91 offset0:128 offset1:144
	ds_write2_b32 v0, v84, v80 offset0:32 offset1:48
	ds_write2_b32 v0, v85, v81 offset0:160 offset1:176
	ds_write2_b32 v1, v86, v82 offset0:32 offset1:48
	ds_write2_b32 v1, v87, v83 offset0:160 offset1:176
	v_add_u32_e32 v1, 0x2000, v0
	v_add_u32_e32 v2, 0x2400, v0
	ds_write2_b32 v1, v76, v72 offset1:16
	ds_write2_b32 v1, v77, v73 offset0:128 offset1:144
	ds_write2_b32 v2, v78, v74 offset1:16
	ds_write2_b32 v2, v79, v75 offset0:128 offset1:144
	ds_write2_b32 v1, v68, v64 offset0:32 offset1:48
	ds_write2_b32 v1, v69, v65 offset0:160 offset1:176
	ds_write2_b32 v2, v70, v66 offset0:32 offset1:48
	ds_write2_b32 v2, v71, v67 offset0:160 offset1:176
	v_add_u32_e32 v1, 0x4000, v0
	v_add_u32_e32 v2, 0x4400, v0
	ds_write2_b32 v1, v60, v56 offset1:16
	ds_write2_b32 v1, v61, v57 offset0:128 offset1:144
	ds_write2_b32 v2, v62, v58 offset1:16
	ds_write2_b32 v2, v63, v59 offset0:128 offset1:144
	ds_write2_b32 v1, v52, v48 offset0:32 offset1:48
	ds_write2_b32 v1, v53, v49 offset0:160 offset1:176
	ds_write2_b32 v2, v54, v50 offset0:32 offset1:48
	ds_write2_b32 v2, v55, v51 offset0:160 offset1:176
	v_add_u32_e32 v1, 0x6000, v0
	v_add_u32_e32 v0, 0x6400, v0
	ds_write2_b32 v1, v44, v40 offset1:16
	ds_write2_b32 v1, v45, v41 offset0:128 offset1:144
	ds_write2_b32 v0, v46, v42 offset1:16
	ds_write2_b32 v0, v47, v43 offset0:128 offset1:144
	ds_write2_b32 v1, v36, v28 offset0:32 offset1:48
	ds_write2_b32 v1, v37, v29 offset0:160 offset1:176
	ds_write2_b32 v0, v38, v30 offset0:32 offset1:48
	ds_write2_b32 v0, v39, v31 offset0:160 offset1:176
	s_waitcnt lgkmcnt(0)
	s_barrier
	s_and_saveexec_b64 s[0:1], s[4:5]
	s_mov_b32 s9, 0x800000
	s_movk_i32 s22, 0xeff
	s_movk_i32 s23, 0x1800
	s_cbranch_execz .LBB0_1382
	v_and_b32_e32 v1, 64, v212
	v_xor_b32_e32 v0, 1, v212
	s_waitcnt vmcnt(6)
	v_add_u32_e32 v4, 64, v1
	v_cmp_lt_i32_e32 vcc, v0, v4
	v_xor_b32_e32 v1, 2, v212
	v_xor_b32_e32 v2, 4, v212
	v_cndmask_b32_e32 v0, v212, v0, vcc
	v_cmp_lt_i32_e32 vcc, v1, v4
	v_xor_b32_e32 v3, 8, v212
	v_xor_b32_e32 v5, 16, v212
	v_cndmask_b32_e32 v1, v212, v1, vcc
	v_cmp_lt_i32_e32 vcc, v2, v4
	v_lshlrev_b32_e32 v0, 2, v0
	v_lshlrev_b32_e32 v1, 2, v1
	v_cndmask_b32_e32 v2, v212, v2, vcc
	v_cmp_lt_i32_e32 vcc, v3, v4
	v_lshlrev_b32_e32 v2, 2, v2
	s_mov_b64 s[10:11], 0
	v_cndmask_b32_e32 v3, v212, v3, vcc
	v_cmp_lt_i32_e32 vcc, v5, v4
	v_lshlrev_b32_e32 v3, 2, v3
	s_nop 0
	v_cndmask_b32_e32 v4, v212, v5, vcc
	v_lshlrev_b32_e32 v4, 2, v4
	v_mov_b32_e32 v5, v124
	v_lshrrev_b32_e32 v14, 5, v124
	v_and_b32_e32 v15, 31, v124
	v_lshlrev_b32_e32 v102, 4, v15
	v_lshl_or_b32 v102, v14, 9, v102
	v_add_u32_e32 v14, s38, v14
	v_mad_i64_i32 v[6:7], s[12:13], v14, s23, v[98:99]
	global_load_dwordx4 v[32:35], v[6:7], off
	v_add_u32_e32 v14, 8, v14
	v_mad_i64_i32 v[6:7], s[12:13], v14, s23, v[98:99]
	global_load_dwordx4 v[36:39], v[6:7], off
	v_add_u32_e32 v14, 8, v14
	v_mad_i64_i32 v[6:7], s[12:13], v14, s23, v[98:99]
	global_load_dwordx4 v[40:43], v[6:7], off
	v_add_u32_e32 v14, 8, v14
	v_mad_i64_i32 v[6:7], s[12:13], v14, s23, v[98:99]
	global_load_dwordx4 v[44:47], v[6:7], off
	v_add_u32_e32 v14, 8, v14
	v_mad_i64_i32 v[6:7], s[12:13], v14, s23, v[98:99]
	global_load_dwordx4 v[48:51], v[6:7], off
	v_add_u32_e32 v14, 8, v14
	v_mad_i64_i32 v[6:7], s[12:13], v14, s23, v[98:99]
	global_load_dwordx4 v[52:55], v[6:7], off
	v_add_u32_e32 v14, 8, v14
	v_mad_i64_i32 v[6:7], s[12:13], v14, s23, v[98:99]
	global_load_dwordx4 v[56:59], v[6:7], off
	v_add_u32_e32 v14, 8, v14
	v_mad_i64_i32 v[6:7], s[12:13], v14, s23, v[98:99]
	global_load_dwordx4 v[60:63], v[6:7], off
	v_add_u32_e32 v14, 8, v14
	v_mad_i64_i32 v[6:7], s[12:13], v14, s23, v[98:99]
	global_load_dwordx4 v[64:67], v[6:7], off
	v_add_u32_e32 v14, 8, v14
	v_mad_i64_i32 v[6:7], s[12:13], v14, s23, v[98:99]
	global_load_dwordx4 v[68:71], v[6:7], off
	v_add_u32_e32 v14, 8, v14
	v_mad_i64_i32 v[6:7], s[12:13], v14, s23, v[98:99]
	global_load_dwordx4 v[72:75], v[6:7], off
	v_add_u32_e32 v14, 8, v14
	v_mad_i64_i32 v[6:7], s[12:13], v14, s23, v[98:99]
	global_load_dwordx4 v[76:79], v[6:7], off
	v_add_u32_e32 v14, 8, v14
	v_mad_i64_i32 v[6:7], s[12:13], v14, s23, v[98:99]
	global_load_dwordx4 v[80:83], v[6:7], off
	v_add_u32_e32 v14, 8, v14
	v_mad_i64_i32 v[6:7], s[12:13], v14, s23, v[98:99]
	global_load_dwordx4 v[84:87], v[6:7], off
	v_add_u32_e32 v14, 8, v14
	v_mad_i64_i32 v[6:7], s[12:13], v14, s23, v[98:99]
	global_load_dwordx4 v[88:91], v[6:7], off
	v_add_u32_e32 v14, 8, v14
	v_mad_i64_i32 v[6:7], s[12:13], v14, s23, v[98:99]
	global_load_dwordx4 v[92:95], v[6:7], off
	s_waitcnt vmcnt(15)
	v_lshlrev_b32_e32 v10, 16, v32
	v_and_b32_e32 v6, 0xffff0000, v32
	v_mul_f32_e32 v13, v6, v6
	v_fmac_f32_e32 v13, v10, v10
	v_lshlrev_b32_e32 v11, 16, v33
	v_and_b32_e32 v10, 0xffff0000, v33
	v_pk_mul_f32 v[6:7], v[10:11], v[10:11]
	v_add_f32_e32 v7, v13, v7
	v_add_f32_e32 v10, v6, v7
	v_lshlrev_b32_e32 v7, 16, v34
	v_and_b32_e32 v6, 0xffff0000, v34
	v_pk_mul_f32 v[6:7], v[6:7], v[6:7]
	v_add_f32_e32 v7, v7, v10
	v_add_f32_e32 v8, v6, v7
	v_lshlrev_b32_e32 v7, 16, v35
	v_and_b32_e32 v6, 0xffff0000, v35
	v_pk_mul_f32 v[6:7], v[6:7], v[6:7]
	v_add_f32_e32 v7, v7, v8
	v_add_f32_e32 v172, v6, v7
	s_waitcnt vmcnt(14)
; DEV float lo2f(u32 w) { return __uint_as_float(w << 16); }
; DEV float hi2f(u32 w) { return __uint_as_float(w & 0xffff0000u); }
;     ...
;       for (int i = tid; i < 128 * 32; i += NTHR) {
;         int r = i >> 5, sub = i & 31, c4 = sub * 4;
;         int row = m0 + r;
;         float ss = 0.f;
;         if (EPI == EPI_Q) {
;           uint4 w = *(const uint4*)(Pm + (size_t)row * LDP + sub * 8);
;           float a;
;           a = lo2f(w.x); ss += a * a; a = hi2f(w.x); ss += a * a; a = lo2f(w.y); ss += a * a; a = hi2f(w.y); ss += a * a;
;           a = lo2f(w.z); ss += a * a; a = hi2f(w.z); ss += a * a; a = lo2f(w.w); ss += a * a; a = hi2f(w.w); ss += a * a;
;         } else {
;           uint2 w = *(const uint2*)(Pm + (size_t)row * LDP + 256 + sub * 4);
;           float a;
;           a = lo2f(w.x); ss += a * a; a = hi2f(w.x); ss += a * a; a = lo2f(w.y); ss += a * a; a = hi2f(w.y); ss += a * a;
;         }
;         ss += __shfl_xor(ss, 1, 64); ss += __shfl_xor(ss, 2, 64); ss += __shfl_xor(ss, 4, 64);
;         ss += __shfl_xor(ss, 8, 64); ss += __shfl_xor(ss, 16, 64);
	v_lshlrev_b32_e32 v10, 16, v36
	v_and_b32_e32 v6, 0xffff0000, v36
	v_mul_f32_e32 v13, v6, v6
	v_fmac_f32_e32 v13, v10, v10
	v_lshlrev_b32_e32 v11, 16, v37
	v_and_b32_e32 v10, 0xffff0000, v37
	v_pk_mul_f32 v[6:7], v[10:11], v[10:11]
	v_add_f32_e32 v7, v13, v7
	v_add_f32_e32 v10, v6, v7
	v_lshlrev_b32_e32 v7, 16, v38
	v_and_b32_e32 v6, 0xffff0000, v38
	v_pk_mul_f32 v[6:7], v[6:7], v[6:7]
	v_add_f32_e32 v7, v7, v10
	v_add_f32_e32 v8, v6, v7
	v_lshlrev_b32_e32 v7, 16, v39
	v_and_b32_e32 v6, 0xffff0000, v39
	v_pk_mul_f32 v[6:7], v[6:7], v[6:7]
	v_add_f32_e32 v7, v7, v8
	v_add_f32_e32 v174, v6, v7
	s_waitcnt vmcnt(13)
	v_lshlrev_b32_e32 v10, 16, v40
	v_and_b32_e32 v6, 0xffff0000, v40
	v_mul_f32_e32 v13, v6, v6
	v_fmac_f32_e32 v13, v10, v10
	v_lshlrev_b32_e32 v11, 16, v41
	v_and_b32_e32 v10, 0xffff0000, v41
	v_pk_mul_f32 v[6:7], v[10:11], v[10:11]
	v_add_f32_e32 v7, v13, v7
	v_add_f32_e32 v10, v6, v7
	v_lshlrev_b32_e32 v7, 16, v42
	v_and_b32_e32 v6, 0xffff0000, v42
	v_pk_mul_f32 v[6:7], v[6:7], v[6:7]
	v_add_f32_e32 v7, v7, v10
	v_add_f32_e32 v8, v6, v7
	v_lshlrev_b32_e32 v7, 16, v43
	v_and_b32_e32 v6, 0xffff0000, v43
	v_pk_mul_f32 v[6:7], v[6:7], v[6:7]
	v_add_f32_e32 v7, v7, v8
	v_add_f32_e32 v176, v6, v7
	s_waitcnt vmcnt(12)
	v_lshlrev_b32_e32 v10, 16, v44
	v_and_b32_e32 v6, 0xffff0000, v44
	v_mul_f32_e32 v13, v6, v6
	v_fmac_f32_e32 v13, v10, v10
	v_lshlrev_b32_e32 v11, 16, v45
	v_and_b32_e32 v10, 0xffff0000, v45
	v_pk_mul_f32 v[6:7], v[10:11], v[10:11]
	v_add_f32_e32 v7, v13, v7
	v_add_f32_e32 v10, v6, v7
	v_lshlrev_b32_e32 v7, 16, v46
	v_and_b32_e32 v6, 0xffff0000, v46
	v_pk_mul_f32 v[6:7], v[6:7], v[6:7]
	v_add_f32_e32 v7, v7, v10
	v_add_f32_e32 v8, v6, v7
	v_lshlrev_b32_e32 v7, 16, v47
	v_and_b32_e32 v6, 0xffff0000, v47
	v_pk_mul_f32 v[6:7], v[6:7], v[6:7]
	v_add_f32_e32 v7, v7, v8
	v_add_f32_e32 v178, v6, v7
	s_waitcnt vmcnt(11)
	v_lshlrev_b32_e32 v10, 16, v48
	v_and_b32_e32 v6, 0xffff0000, v48
	v_mul_f32_e32 v13, v6, v6
	v_fmac_f32_e32 v13, v10, v10
	v_lshlrev_b32_e32 v11, 16, v49
	v_and_b32_e32 v10, 0xffff0000, v49
	v_pk_mul_f32 v[6:7], v[10:11], v[10:11]
	v_add_f32_e32 v7, v13, v7
	v_add_f32_e32 v10, v6, v7
	v_lshlrev_b32_e32 v7, 16, v50
	v_and_b32_e32 v6, 0xffff0000, v50
	v_pk_mul_f32 v[6:7], v[6:7], v[6:7]
	v_add_f32_e32 v7, v7, v10
	v_add_f32_e32 v8, v6, v7
	v_lshlrev_b32_e32 v7, 16, v51
	v_and_b32_e32 v6, 0xffff0000, v51
	v_pk_mul_f32 v[6:7], v[6:7], v[6:7]
	v_add_f32_e32 v7, v7, v8
	v_add_f32_e32 v180, v6, v7
	s_waitcnt vmcnt(10)
	v_lshlrev_b32_e32 v10, 16, v52
	v_and_b32_e32 v6, 0xffff0000, v52
	v_mul_f32_e32 v13, v6, v6
	v_fmac_f32_e32 v13, v10, v10
	v_lshlrev_b32_e32 v11, 16, v53
	v_and_b32_e32 v10, 0xffff0000, v53
	v_pk_mul_f32 v[6:7], v[10:11], v[10:11]
	v_add_f32_e32 v7, v13, v7
	v_add_f32_e32 v10, v6, v7
	v_lshlrev_b32_e32 v7, 16, v54
	v_and_b32_e32 v6, 0xffff0000, v54
	v_pk_mul_f32 v[6:7], v[6:7], v[6:7]
	v_add_f32_e32 v7, v7, v10
	v_add_f32_e32 v8, v6, v7
	v_lshlrev_b32_e32 v7, 16, v55
	v_and_b32_e32 v6, 0xffff0000, v55
	v_pk_mul_f32 v[6:7], v[6:7], v[6:7]
	v_add_f32_e32 v7, v7, v8
	v_add_f32_e32 v182, v6, v7
	s_waitcnt vmcnt(9)
	v_lshlrev_b32_e32 v10, 16, v56
	v_and_b32_e32 v6, 0xffff0000, v56
	v_mul_f32_e32 v13, v6, v6
	v_fmac_f32_e32 v13, v10, v10
	v_lshlrev_b32_e32 v11, 16, v57
	v_and_b32_e32 v10, 0xffff0000, v57
	v_pk_mul_f32 v[6:7], v[10:11], v[10:11]
	v_add_f32_e32 v7, v13, v7
	v_add_f32_e32 v10, v6, v7
	v_lshlrev_b32_e32 v7, 16, v58
	v_and_b32_e32 v6, 0xffff0000, v58
	v_pk_mul_f32 v[6:7], v[6:7], v[6:7]
	v_add_f32_e32 v7, v7, v10
	v_add_f32_e32 v8, v6, v7
	v_lshlrev_b32_e32 v7, 16, v59
	v_and_b32_e32 v6, 0xffff0000, v59
	v_pk_mul_f32 v[6:7], v[6:7], v[6:7]
	v_add_f32_e32 v7, v7, v8
	v_add_f32_e32 v184, v6, v7
	s_waitcnt vmcnt(8)
	v_lshlrev_b32_e32 v10, 16, v60
	v_and_b32_e32 v6, 0xffff0000, v60
	v_mul_f32_e32 v13, v6, v6
	v_fmac_f32_e32 v13, v10, v10
	v_lshlrev_b32_e32 v11, 16, v61
	v_and_b32_e32 v10, 0xffff0000, v61
	v_pk_mul_f32 v[6:7], v[10:11], v[10:11]
	v_add_f32_e32 v7, v13, v7
	v_add_f32_e32 v10, v6, v7
	v_lshlrev_b32_e32 v7, 16, v62
	v_and_b32_e32 v6, 0xffff0000, v62
	v_pk_mul_f32 v[6:7], v[6:7], v[6:7]
	v_add_f32_e32 v7, v7, v10
	v_add_f32_e32 v8, v6, v7
	v_lshlrev_b32_e32 v7, 16, v63
	v_and_b32_e32 v6, 0xffff0000, v63
	v_pk_mul_f32 v[6:7], v[6:7], v[6:7]
	v_add_f32_e32 v7, v7, v8
	v_add_f32_e32 v186, v6, v7
	s_waitcnt vmcnt(7)
	v_lshlrev_b32_e32 v10, 16, v64
	v_and_b32_e32 v6, 0xffff0000, v64
	v_mul_f32_e32 v13, v6, v6
	v_fmac_f32_e32 v13, v10, v10
	v_lshlrev_b32_e32 v11, 16, v65
	v_and_b32_e32 v10, 0xffff0000, v65
	v_pk_mul_f32 v[6:7], v[10:11], v[10:11]
	v_add_f32_e32 v7, v13, v7
	v_add_f32_e32 v10, v6, v7
	v_lshlrev_b32_e32 v7, 16, v66
	v_and_b32_e32 v6, 0xffff0000, v66
	v_pk_mul_f32 v[6:7], v[6:7], v[6:7]
	v_add_f32_e32 v7, v7, v10
	v_add_f32_e32 v8, v6, v7
	v_lshlrev_b32_e32 v7, 16, v67
	v_and_b32_e32 v6, 0xffff0000, v67
	v_pk_mul_f32 v[6:7], v[6:7], v[6:7]
	v_add_f32_e32 v7, v7, v8
	v_add_f32_e32 v188, v6, v7
	s_waitcnt vmcnt(6)
	v_lshlrev_b32_e32 v10, 16, v68
	v_and_b32_e32 v6, 0xffff0000, v68
	v_mul_f32_e32 v13, v6, v6
	v_fmac_f32_e32 v13, v10, v10
	v_lshlrev_b32_e32 v11, 16, v69
	v_and_b32_e32 v10, 0xffff0000, v69
	v_pk_mul_f32 v[6:7], v[10:11], v[10:11]
	v_add_f32_e32 v7, v13, v7
	v_add_f32_e32 v10, v6, v7
	v_lshlrev_b32_e32 v7, 16, v70
	v_and_b32_e32 v6, 0xffff0000, v70
	v_pk_mul_f32 v[6:7], v[6:7], v[6:7]
	v_add_f32_e32 v7, v7, v10
	v_add_f32_e32 v8, v6, v7
	v_lshlrev_b32_e32 v7, 16, v71
	v_and_b32_e32 v6, 0xffff0000, v71
	v_pk_mul_f32 v[6:7], v[6:7], v[6:7]
	v_add_f32_e32 v7, v7, v8
	v_add_f32_e32 v190, v6, v7
	s_waitcnt vmcnt(5)
; DEV float lo2f(u32 w) { return __uint_as_float(w << 16); }
; DEV float hi2f(u32 w) { return __uint_as_float(w & 0xffff0000u); }
;     ...
;           a = lo2f(w.x); ss += a * a; a = hi2f(w.x); ss += a * a; a = lo2f(w.y); ss += a * a; a = hi2f(w.y); ss += a * a;
;           a = lo2f(w.z); ss += a * a; a = hi2f(w.z); ss += a * a; a = lo2f(w.w); ss += a * a; a = hi2f(w.w); ss += a * a;
;         } else {
;           uint2 w = *(const uint2*)(Pm + (size_t)row * LDP + 256 + sub * 4);
;           float a;
;           a = lo2f(w.x); ss += a * a; a = hi2f(w.x); ss += a * a; a = lo2f(w.y); ss += a * a; a = hi2f(w.y); ss += a * a;
;         }
;         ss += __shfl_xor(ss, 1, 64); ss += __shfl_xor(ss, 2, 64); ss += __shfl_xor(ss, 4, 64);
;         ss += __shfl_xor(ss, 8, 64); ss += __shfl_xor(ss, 16, 64);
	v_lshlrev_b32_e32 v10, 16, v72
	v_and_b32_e32 v6, 0xffff0000, v72
	v_mul_f32_e32 v13, v6, v6
	v_fmac_f32_e32 v13, v10, v10
	v_lshlrev_b32_e32 v11, 16, v73
	v_and_b32_e32 v10, 0xffff0000, v73
	v_pk_mul_f32 v[6:7], v[10:11], v[10:11]
	v_add_f32_e32 v7, v13, v7
	v_add_f32_e32 v10, v6, v7
	v_lshlrev_b32_e32 v7, 16, v74
	v_and_b32_e32 v6, 0xffff0000, v74
	v_pk_mul_f32 v[6:7], v[6:7], v[6:7]
	v_add_f32_e32 v7, v7, v10
	v_add_f32_e32 v8, v6, v7
	v_lshlrev_b32_e32 v7, 16, v75
	v_and_b32_e32 v6, 0xffff0000, v75
	v_pk_mul_f32 v[6:7], v[6:7], v[6:7]
	v_add_f32_e32 v7, v7, v8
	v_add_f32_e32 v192, v6, v7
	s_waitcnt vmcnt(4)
	v_lshlrev_b32_e32 v10, 16, v76
	v_and_b32_e32 v6, 0xffff0000, v76
	v_mul_f32_e32 v13, v6, v6
	v_fmac_f32_e32 v13, v10, v10
	v_lshlrev_b32_e32 v11, 16, v77
	v_and_b32_e32 v10, 0xffff0000, v77
	v_pk_mul_f32 v[6:7], v[10:11], v[10:11]
	v_add_f32_e32 v7, v13, v7
	v_add_f32_e32 v10, v6, v7
	v_lshlrev_b32_e32 v7, 16, v78
	v_and_b32_e32 v6, 0xffff0000, v78
	v_pk_mul_f32 v[6:7], v[6:7], v[6:7]
	v_add_f32_e32 v7, v7, v10
	v_add_f32_e32 v8, v6, v7
	v_lshlrev_b32_e32 v7, 16, v79
	v_and_b32_e32 v6, 0xffff0000, v79
	v_pk_mul_f32 v[6:7], v[6:7], v[6:7]
	v_add_f32_e32 v7, v7, v8
	v_add_f32_e32 v194, v6, v7
	s_waitcnt vmcnt(3)
	v_lshlrev_b32_e32 v10, 16, v80
	v_and_b32_e32 v6, 0xffff0000, v80
	v_mul_f32_e32 v13, v6, v6
	v_fmac_f32_e32 v13, v10, v10
	v_lshlrev_b32_e32 v11, 16, v81
	v_and_b32_e32 v10, 0xffff0000, v81
	v_pk_mul_f32 v[6:7], v[10:11], v[10:11]
	v_add_f32_e32 v7, v13, v7
	v_add_f32_e32 v10, v6, v7
	v_lshlrev_b32_e32 v7, 16, v82
	v_and_b32_e32 v6, 0xffff0000, v82
	v_pk_mul_f32 v[6:7], v[6:7], v[6:7]
	v_add_f32_e32 v7, v7, v10
	v_add_f32_e32 v8, v6, v7
	v_lshlrev_b32_e32 v7, 16, v83
	v_and_b32_e32 v6, 0xffff0000, v83
	v_pk_mul_f32 v[6:7], v[6:7], v[6:7]
	v_add_f32_e32 v7, v7, v8
	v_add_f32_e32 v196, v6, v7
	s_waitcnt vmcnt(2)
	v_lshlrev_b32_e32 v10, 16, v84
	v_and_b32_e32 v6, 0xffff0000, v84
	v_mul_f32_e32 v13, v6, v6
	v_fmac_f32_e32 v13, v10, v10
	v_lshlrev_b32_e32 v11, 16, v85
	v_and_b32_e32 v10, 0xffff0000, v85
	v_pk_mul_f32 v[6:7], v[10:11], v[10:11]
	v_add_f32_e32 v7, v13, v7
	v_add_f32_e32 v10, v6, v7
	v_lshlrev_b32_e32 v7, 16, v86
	v_and_b32_e32 v6, 0xffff0000, v86
	v_pk_mul_f32 v[6:7], v[6:7], v[6:7]
	v_add_f32_e32 v7, v7, v10
	v_add_f32_e32 v8, v6, v7
	v_lshlrev_b32_e32 v7, 16, v87
	v_and_b32_e32 v6, 0xffff0000, v87
	v_pk_mul_f32 v[6:7], v[6:7], v[6:7]
	v_add_f32_e32 v7, v7, v8
	v_add_f32_e32 v198, v6, v7
	s_waitcnt vmcnt(1)
	v_lshlrev_b32_e32 v10, 16, v88
	v_and_b32_e32 v6, 0xffff0000, v88
	v_mul_f32_e32 v13, v6, v6
	v_fmac_f32_e32 v13, v10, v10
	v_lshlrev_b32_e32 v11, 16, v89
	v_and_b32_e32 v10, 0xffff0000, v89
	v_pk_mul_f32 v[6:7], v[10:11], v[10:11]
	v_add_f32_e32 v7, v13, v7
	v_add_f32_e32 v10, v6, v7
	v_lshlrev_b32_e32 v7, 16, v90
	v_and_b32_e32 v6, 0xffff0000, v90
	v_pk_mul_f32 v[6:7], v[6:7], v[6:7]
	v_add_f32_e32 v7, v7, v10
	v_add_f32_e32 v8, v6, v7
	v_lshlrev_b32_e32 v7, 16, v91
	v_and_b32_e32 v6, 0xffff0000, v91
	v_pk_mul_f32 v[6:7], v[6:7], v[6:7]
	v_add_f32_e32 v7, v7, v8
	v_add_f32_e32 v200, v6, v7
	s_waitcnt vmcnt(0)
	v_lshlrev_b32_e32 v10, 16, v92
	v_and_b32_e32 v6, 0xffff0000, v92
	v_mul_f32_e32 v13, v6, v6
	v_fmac_f32_e32 v13, v10, v10
	v_lshlrev_b32_e32 v11, 16, v93
	v_and_b32_e32 v10, 0xffff0000, v93
	v_pk_mul_f32 v[6:7], v[10:11], v[10:11]
	v_add_f32_e32 v7, v13, v7
	v_add_f32_e32 v10, v6, v7
	v_lshlrev_b32_e32 v7, 16, v94
	v_and_b32_e32 v6, 0xffff0000, v94
	v_pk_mul_f32 v[6:7], v[6:7], v[6:7]
	v_add_f32_e32 v7, v7, v10
	v_add_f32_e32 v8, v6, v7
	v_lshlrev_b32_e32 v7, 16, v95
	v_and_b32_e32 v6, 0xffff0000, v95
	v_pk_mul_f32 v[6:7], v[6:7], v[6:7]
	v_add_f32_e32 v7, v7, v8
	v_add_f32_e32 v202, v6, v7
	ds_bpermute_b32 v173, v0, v172
	ds_bpermute_b32 v175, v0, v174
	ds_bpermute_b32 v177, v0, v176
	ds_bpermute_b32 v179, v0, v178
	ds_bpermute_b32 v181, v0, v180
	ds_bpermute_b32 v183, v0, v182
	ds_bpermute_b32 v185, v0, v184
	ds_bpermute_b32 v187, v0, v186
	s_waitcnt lgkmcnt(7)
	v_add_f32_e32 v172, v172, v173
	ds_bpermute_b32 v189, v0, v188
	s_waitcnt lgkmcnt(7)
	v_add_f32_e32 v174, v174, v175
	ds_bpermute_b32 v191, v0, v190
	s_waitcnt lgkmcnt(7)
	v_add_f32_e32 v176, v176, v177
	ds_bpermute_b32 v193, v0, v192
	s_waitcnt lgkmcnt(7)
	v_add_f32_e32 v178, v178, v179
	ds_bpermute_b32 v195, v0, v194
	s_waitcnt lgkmcnt(7)
	v_add_f32_e32 v180, v180, v181
	ds_bpermute_b32 v197, v0, v196
	s_waitcnt lgkmcnt(7)
	v_add_f32_e32 v182, v182, v183
	ds_bpermute_b32 v199, v0, v198
	s_waitcnt lgkmcnt(7)
	v_add_f32_e32 v184, v184, v185
	ds_bpermute_b32 v201, v0, v200
	s_waitcnt lgkmcnt(7)
	v_add_f32_e32 v186, v186, v187
	ds_bpermute_b32 v203, v0, v202
	s_waitcnt lgkmcnt(7)
	v_add_f32_e32 v188, v188, v189
	s_waitcnt lgkmcnt(6)
	v_add_f32_e32 v190, v190, v191
	s_waitcnt lgkmcnt(5)
	v_add_f32_e32 v192, v192, v193
	s_waitcnt lgkmcnt(4)
	v_add_f32_e32 v194, v194, v195
	s_waitcnt lgkmcnt(3)
	v_add_f32_e32 v196, v196, v197
	s_waitcnt lgkmcnt(2)
	v_add_f32_e32 v198, v198, v199
	s_waitcnt lgkmcnt(1)
	v_add_f32_e32 v200, v200, v201
	s_waitcnt lgkmcnt(0)
	v_add_f32_e32 v202, v202, v203
	ds_bpermute_b32 v173, v1, v172
	ds_bpermute_b32 v175, v1, v174
	ds_bpermute_b32 v177, v1, v176
	ds_bpermute_b32 v179, v1, v178
	ds_bpermute_b32 v181, v1, v180
	ds_bpermute_b32 v183, v1, v182
	ds_bpermute_b32 v185, v1, v184
	ds_bpermute_b32 v187, v1, v186
	s_waitcnt lgkmcnt(7)
	v_add_f32_e32 v172, v172, v173
	ds_bpermute_b32 v189, v1, v188
	s_waitcnt lgkmcnt(7)
	v_add_f32_e32 v174, v174, v175
	ds_bpermute_b32 v191, v1, v190
	s_waitcnt lgkmcnt(7)
	v_add_f32_e32 v176, v176, v177
	ds_bpermute_b32 v193, v1, v192
	s_waitcnt lgkmcnt(7)
;     ...
;         ss += __shfl_xor(ss, 1, 64); ss += __shfl_xor(ss, 2, 64); ss += __shfl_xor(ss, 4, 64);
;         ss += __shfl_xor(ss, 8, 64); ss += __shfl_xor(ss, 16, 64);
	v_add_f32_e32 v178, v178, v179
	ds_bpermute_b32 v195, v1, v194
	s_waitcnt lgkmcnt(7)
	v_add_f32_e32 v180, v180, v181
	ds_bpermute_b32 v197, v1, v196
	s_waitcnt lgkmcnt(7)
	v_add_f32_e32 v182, v182, v183
	ds_bpermute_b32 v199, v1, v198
	s_waitcnt lgkmcnt(7)
	v_add_f32_e32 v184, v184, v185
	ds_bpermute_b32 v201, v1, v200
	s_waitcnt lgkmcnt(7)
	v_add_f32_e32 v186, v186, v187
	ds_bpermute_b32 v203, v1, v202
	s_waitcnt lgkmcnt(7)
	v_add_f32_e32 v188, v188, v189
	s_waitcnt lgkmcnt(6)
	v_add_f32_e32 v190, v190, v191
	s_waitcnt lgkmcnt(5)
	v_add_f32_e32 v192, v192, v193
	s_waitcnt lgkmcnt(4)
	v_add_f32_e32 v194, v194, v195
	s_waitcnt lgkmcnt(3)
	v_add_f32_e32 v196, v196, v197
	s_waitcnt lgkmcnt(2)
	v_add_f32_e32 v198, v198, v199
	s_waitcnt lgkmcnt(1)
	v_add_f32_e32 v200, v200, v201
	s_waitcnt lgkmcnt(0)
	v_add_f32_e32 v202, v202, v203
	ds_bpermute_b32 v173, v2, v172
	ds_bpermute_b32 v175, v2, v174
	ds_bpermute_b32 v177, v2, v176
	ds_bpermute_b32 v179, v2, v178
	ds_bpermute_b32 v181, v2, v180
	ds_bpermute_b32 v183, v2, v182
	ds_bpermute_b32 v185, v2, v184
	ds_bpermute_b32 v187, v2, v186
	s_waitcnt lgkmcnt(7)
	v_add_f32_e32 v172, v172, v173
	ds_bpermute_b32 v189, v2, v188
	s_waitcnt lgkmcnt(7)
	v_add_f32_e32 v174, v174, v175
	ds_bpermute_b32 v191, v2, v190
	s_waitcnt lgkmcnt(7)
	v_add_f32_e32 v176, v176, v177
	ds_bpermute_b32 v193, v2, v192
	s_waitcnt lgkmcnt(7)
	v_add_f32_e32 v178, v178, v179
	ds_bpermute_b32 v195, v2, v194
	s_waitcnt lgkmcnt(7)
	v_add_f32_e32 v180, v180, v181
	ds_bpermute_b32 v197, v2, v196
	s_waitcnt lgkmcnt(7)
	v_add_f32_e32 v182, v182, v183
	ds_bpermute_b32 v199, v2, v198
	s_waitcnt lgkmcnt(7)
	v_add_f32_e32 v184, v184, v185
	ds_bpermute_b32 v201, v2, v200
	s_waitcnt lgkmcnt(7)
	v_add_f32_e32 v186, v186, v187
	ds_bpermute_b32 v203, v2, v202
	s_waitcnt lgkmcnt(7)
	v_add_f32_e32 v188, v188, v189
	s_waitcnt lgkmcnt(6)
	v_add_f32_e32 v190, v190, v191
	s_waitcnt lgkmcnt(5)
	v_add_f32_e32 v192, v192, v193
	s_waitcnt lgkmcnt(4)
	v_add_f32_e32 v194, v194, v195
	s_waitcnt lgkmcnt(3)
	v_add_f32_e32 v196, v196, v197
	s_waitcnt lgkmcnt(2)
	v_add_f32_e32 v198, v198, v199
	s_waitcnt lgkmcnt(1)
	v_add_f32_e32 v200, v200, v201
	s_waitcnt lgkmcnt(0)
	v_add_f32_e32 v202, v202, v203
	ds_bpermute_b32 v173, v3, v172
	ds_bpermute_b32 v175, v3, v174
	ds_bpermute_b32 v177, v3, v176
	ds_bpermute_b32 v179, v3, v178
	ds_bpermute_b32 v181, v3, v180
	ds_bpermute_b32 v183, v3, v182
	ds_bpermute_b32 v185, v3, v184
	ds_bpermute_b32 v187, v3, v186
	s_waitcnt lgkmcnt(7)
	v_add_f32_e32 v172, v172, v173
	ds_bpermute_b32 v189, v3, v188
	s_waitcnt lgkmcnt(7)
	v_add_f32_e32 v174, v174, v175
	ds_bpermute_b32 v191, v3, v190
	s_waitcnt lgkmcnt(7)
	v_add_f32_e32 v176, v176, v177
	ds_bpermute_b32 v193, v3, v192
	s_waitcnt lgkmcnt(7)
	v_add_f32_e32 v178, v178, v179
	ds_bpermute_b32 v195, v3, v194
	s_waitcnt lgkmcnt(7)
	v_add_f32_e32 v180, v180, v181
	ds_bpermute_b32 v197, v3, v196
	s_waitcnt lgkmcnt(7)
	v_add_f32_e32 v182, v182, v183
	ds_bpermute_b32 v199, v3, v198
	s_waitcnt lgkmcnt(7)
	v_add_f32_e32 v184, v184, v185
	ds_bpermute_b32 v201, v3, v200
	s_waitcnt lgkmcnt(7)
	v_add_f32_e32 v186, v186, v187
	ds_bpermute_b32 v203, v3, v202
	s_waitcnt lgkmcnt(7)
	v_add_f32_e32 v188, v188, v189
	s_waitcnt lgkmcnt(6)
	v_add_f32_e32 v190, v190, v191
	s_waitcnt lgkmcnt(5)
	v_add_f32_e32 v192, v192, v193
	s_waitcnt lgkmcnt(4)
	v_add_f32_e32 v194, v194, v195
	s_waitcnt lgkmcnt(3)
	v_add_f32_e32 v196, v196, v197
	s_waitcnt lgkmcnt(2)
	v_add_f32_e32 v198, v198, v199
	s_waitcnt lgkmcnt(1)
	v_add_f32_e32 v200, v200, v201
	s_waitcnt lgkmcnt(0)
	v_add_f32_e32 v202, v202, v203
	ds_bpermute_b32 v173, v4, v172
	ds_bpermute_b32 v175, v4, v174
	ds_bpermute_b32 v177, v4, v176
	ds_bpermute_b32 v179, v4, v178
	ds_bpermute_b32 v181, v4, v180
	ds_bpermute_b32 v183, v4, v182
	ds_bpermute_b32 v185, v4, v184
	ds_bpermute_b32 v187, v4, v186
	s_waitcnt lgkmcnt(7)
	v_add_f32_e32 v172, v172, v173
	ds_bpermute_b32 v189, v4, v188
	s_waitcnt lgkmcnt(7)
	v_add_f32_e32 v174, v174, v175
	ds_bpermute_b32 v191, v4, v190
	s_waitcnt lgkmcnt(7)
	v_add_f32_e32 v176, v176, v177
	ds_bpermute_b32 v193, v4, v192
	s_waitcnt lgkmcnt(7)
	v_add_f32_e32 v178, v178, v179
	ds_bpermute_b32 v195, v4, v194
	s_waitcnt lgkmcnt(7)
	v_add_f32_e32 v180, v180, v181
	ds_bpermute_b32 v197, v4, v196
	s_waitcnt lgkmcnt(7)
	v_add_f32_e32 v182, v182, v183
	ds_bpermute_b32 v199, v4, v198
	s_waitcnt lgkmcnt(7)
	v_add_f32_e32 v184, v184, v185
	ds_bpermute_b32 v201, v4, v200
	s_waitcnt lgkmcnt(7)
	v_add_f32_e32 v186, v186, v187
	ds_bpermute_b32 v203, v4, v202
	s_waitcnt lgkmcnt(7)
	v_add_f32_e32 v188, v188, v189
	s_waitcnt lgkmcnt(6)
	v_add_f32_e32 v190, v190, v191
	s_waitcnt lgkmcnt(5)
	v_add_f32_e32 v192, v192, v193
	s_waitcnt lgkmcnt(4)
	v_add_f32_e32 v194, v194, v195
	s_waitcnt lgkmcnt(3)
	v_add_f32_e32 v196, v196, v197
	s_waitcnt lgkmcnt(2)
	v_add_f32_e32 v198, v198, v199
	s_waitcnt lgkmcnt(1)
	v_add_f32_e32 v200, v200, v201
	s_waitcnt lgkmcnt(0)
;     ...
;         ss += __shfl_xor(ss, 1, 64); ss += __shfl_xor(ss, 2, 64); ss += __shfl_xor(ss, 4, 64);
;         ss += __shfl_xor(ss, 8, 64); ss += __shfl_xor(ss, 16, 64);
;         float rinv = (EPI == EPI_Q) ? rsqrtf(ss * (1.f / 256.f) + 1e-6f) * (0.10206207261596577f * 1.4426950408889634f)
;                                     : rsqrtf(ss * (1.f / 128.f) + 1e-6f);
;         float4 v = *(float4*)(sC + r * 128 + c4);
;         v.x *= rinv; v.y *= rinv; v.z *= rinv; v.w *= rinv;
;         *(float4*)(sC + r * 128 + c4) = v;
	v_add_f32_e32 v202, v202, v203
	v_fmamk_f32 v6, v172, 0x3b800000, v211
	v_cmp_gt_f32_e32 vcc, s9, v6
	v_mul_f32_e32 v7, 0x4b800000, v6
	s_nop 0
	v_cndmask_b32_e32 v6, v6, v7, vcc
	v_rsq_f32_e32 v6, v6
	s_nop 0
	v_mul_f32_e32 v7, 0x45800000, v6
	v_cndmask_b32_e32 v6, v6, v7, vcc
	v_mul_f32_e32 v172, 0x3e16c740, v6
	v_fmamk_f32 v6, v174, 0x3b800000, v211
	v_cmp_gt_f32_e32 vcc, s9, v6
	v_mul_f32_e32 v7, 0x4b800000, v6
	s_nop 0
	v_cndmask_b32_e32 v6, v6, v7, vcc
	v_rsq_f32_e32 v6, v6
	s_nop 0
	v_mul_f32_e32 v7, 0x45800000, v6
	v_cndmask_b32_e32 v6, v6, v7, vcc
	v_mul_f32_e32 v174, 0x3e16c740, v6
	v_fmamk_f32 v6, v176, 0x3b800000, v211
	v_cmp_gt_f32_e32 vcc, s9, v6
	v_mul_f32_e32 v7, 0x4b800000, v6
	s_nop 0
	v_cndmask_b32_e32 v6, v6, v7, vcc
	v_rsq_f32_e32 v6, v6
	s_nop 0
	v_mul_f32_e32 v7, 0x45800000, v6
	v_cndmask_b32_e32 v6, v6, v7, vcc
	v_mul_f32_e32 v176, 0x3e16c740, v6
	v_fmamk_f32 v6, v178, 0x3b800000, v211
	v_cmp_gt_f32_e32 vcc, s9, v6
	v_mul_f32_e32 v7, 0x4b800000, v6
	s_nop 0
	v_cndmask_b32_e32 v6, v6, v7, vcc
	v_rsq_f32_e32 v6, v6
	s_nop 0
	v_mul_f32_e32 v7, 0x45800000, v6
	v_cndmask_b32_e32 v6, v6, v7, vcc
	v_mul_f32_e32 v178, 0x3e16c740, v6
	v_fmamk_f32 v6, v180, 0x3b800000, v211
	v_cmp_gt_f32_e32 vcc, s9, v6
	v_mul_f32_e32 v7, 0x4b800000, v6
	s_nop 0
	v_cndmask_b32_e32 v6, v6, v7, vcc
	v_rsq_f32_e32 v6, v6
	s_nop 0
	v_mul_f32_e32 v7, 0x45800000, v6
	v_cndmask_b32_e32 v6, v6, v7, vcc
	v_mul_f32_e32 v180, 0x3e16c740, v6
	v_fmamk_f32 v6, v182, 0x3b800000, v211
	v_cmp_gt_f32_e32 vcc, s9, v6
	v_mul_f32_e32 v7, 0x4b800000, v6
	s_nop 0
	v_cndmask_b32_e32 v6, v6, v7, vcc
	v_rsq_f32_e32 v6, v6
	s_nop 0
	v_mul_f32_e32 v7, 0x45800000, v6
	v_cndmask_b32_e32 v6, v6, v7, vcc
	v_mul_f32_e32 v182, 0x3e16c740, v6
	v_fmamk_f32 v6, v184, 0x3b800000, v211
	v_cmp_gt_f32_e32 vcc, s9, v6
	v_mul_f32_e32 v7, 0x4b800000, v6
	s_nop 0
	v_cndmask_b32_e32 v6, v6, v7, vcc
	v_rsq_f32_e32 v6, v6
	s_nop 0
	v_mul_f32_e32 v7, 0x45800000, v6
	v_cndmask_b32_e32 v6, v6, v7, vcc
	v_mul_f32_e32 v184, 0x3e16c740, v6
	v_fmamk_f32 v6, v186, 0x3b800000, v211
	v_cmp_gt_f32_e32 vcc, s9, v6
	v_mul_f32_e32 v7, 0x4b800000, v6
	s_nop 0
	v_cndmask_b32_e32 v6, v6, v7, vcc
	v_rsq_f32_e32 v6, v6
	s_nop 0
	v_mul_f32_e32 v7, 0x45800000, v6
	v_cndmask_b32_e32 v6, v6, v7, vcc
	v_mul_f32_e32 v186, 0x3e16c740, v6
	v_fmamk_f32 v6, v188, 0x3b800000, v211
	v_cmp_gt_f32_e32 vcc, s9, v6
	v_mul_f32_e32 v7, 0x4b800000, v6
	s_nop 0
	v_cndmask_b32_e32 v6, v6, v7, vcc
	v_rsq_f32_e32 v6, v6
	s_nop 0
	v_mul_f32_e32 v7, 0x45800000, v6
	v_cndmask_b32_e32 v6, v6, v7, vcc
	v_mul_f32_e32 v188, 0x3e16c740, v6
	v_fmamk_f32 v6, v190, 0x3b800000, v211
	v_cmp_gt_f32_e32 vcc, s9, v6
	v_mul_f32_e32 v7, 0x4b800000, v6
	s_nop 0
	v_cndmask_b32_e32 v6, v6, v7, vcc
	v_rsq_f32_e32 v6, v6
	s_nop 0
	v_mul_f32_e32 v7, 0x45800000, v6
	v_cndmask_b32_e32 v6, v6, v7, vcc
	v_mul_f32_e32 v190, 0x3e16c740, v6
	v_fmamk_f32 v6, v192, 0x3b800000, v211
	v_cmp_gt_f32_e32 vcc, s9, v6
	v_mul_f32_e32 v7, 0x4b800000, v6
	s_nop 0
	v_cndmask_b32_e32 v6, v6, v7, vcc
	v_rsq_f32_e32 v6, v6
	s_nop 0
	v_mul_f32_e32 v7, 0x45800000, v6
	v_cndmask_b32_e32 v6, v6, v7, vcc
	v_mul_f32_e32 v192, 0x3e16c740, v6
	v_fmamk_f32 v6, v194, 0x3b800000, v211
	v_cmp_gt_f32_e32 vcc, s9, v6
	v_mul_f32_e32 v7, 0x4b800000, v6
	s_nop 0
	v_cndmask_b32_e32 v6, v6, v7, vcc
	v_rsq_f32_e32 v6, v6
	s_nop 0
	v_mul_f32_e32 v7, 0x45800000, v6
	v_cndmask_b32_e32 v6, v6, v7, vcc
	v_mul_f32_e32 v194, 0x3e16c740, v6
	v_fmamk_f32 v6, v196, 0x3b800000, v211
	v_cmp_gt_f32_e32 vcc, s9, v6
	v_mul_f32_e32 v7, 0x4b800000, v6
	s_nop 0
	v_cndmask_b32_e32 v6, v6, v7, vcc
	v_rsq_f32_e32 v6, v6
	s_nop 0
	v_mul_f32_e32 v7, 0x45800000, v6
	v_cndmask_b32_e32 v6, v6, v7, vcc
	v_mul_f32_e32 v196, 0x3e16c740, v6
	v_fmamk_f32 v6, v198, 0x3b800000, v211
	v_cmp_gt_f32_e32 vcc, s9, v6
	v_mul_f32_e32 v7, 0x4b800000, v6
	s_nop 0
	v_cndmask_b32_e32 v6, v6, v7, vcc
	v_rsq_f32_e32 v6, v6
	s_nop 0
	v_mul_f32_e32 v7, 0x45800000, v6
	v_cndmask_b32_e32 v6, v6, v7, vcc
	v_mul_f32_e32 v198, 0x3e16c740, v6
	v_fmamk_f32 v6, v200, 0x3b800000, v211
	v_cmp_gt_f32_e32 vcc, s9, v6
	v_mul_f32_e32 v7, 0x4b800000, v6
	s_nop 0
	v_cndmask_b32_e32 v6, v6, v7, vcc
	v_rsq_f32_e32 v6, v6
	s_nop 0
	v_mul_f32_e32 v7, 0x45800000, v6
	v_cndmask_b32_e32 v6, v6, v7, vcc
	v_mul_f32_e32 v200, 0x3e16c740, v6
	v_fmamk_f32 v6, v202, 0x3b800000, v211
	v_cmp_gt_f32_e32 vcc, s9, v6
	v_mul_f32_e32 v7, 0x4b800000, v6
	s_nop 0
	v_cndmask_b32_e32 v6, v6, v7, vcc
	v_rsq_f32_e32 v6, v6
	s_nop 0
	v_mul_f32_e32 v7, 0x45800000, v6
	v_cndmask_b32_e32 v6, v6, v7, vcc
	v_mul_f32_e32 v202, 0x3e16c740, v6
	ds_read_b128 v[32:35], v102 offset:0
	ds_read_b128 v[36:39], v102 offset:4096
	ds_read_b128 v[40:43], v102 offset:8192
	ds_read_b128 v[44:47], v102 offset:12288
	ds_read_b128 v[48:51], v102 offset:16384
	ds_read_b128 v[52:55], v102 offset:20480
	ds_read_b128 v[56:59], v102 offset:24576
	ds_read_b128 v[60:63], v102 offset:28672
	s_waitcnt lgkmcnt(7)
	v_pk_mul_f32 v[32:33], v[32:33], v[172:173] op_sel_hi:[1,0]
	v_pk_mul_f32 v[34:35], v[34:35], v[172:173] op_sel_hi:[1,0]
	ds_write_b128 v102, v[32:35] offset:0
	ds_read_b128 v[64:67], v102 offset:32768
	s_waitcnt lgkmcnt(8)
	v_pk_mul_f32 v[36:37], v[36:37], v[174:175] op_sel_hi:[1,0]
	v_pk_mul_f32 v[38:39], v[38:39], v[174:175] op_sel_hi:[1,0]
	ds_write_b128 v102, v[36:39] offset:4096
	ds_read_b128 v[68:71], v102 offset:36864
	s_waitcnt lgkmcnt(9)
	v_pk_mul_f32 v[40:41], v[40:41], v[176:177] op_sel_hi:[1,0]
	v_pk_mul_f32 v[42:43], v[42:43], v[176:177] op_sel_hi:[1,0]
	ds_write_b128 v102, v[40:43] offset:8192
	ds_read_b128 v[72:75], v102 offset:40960
	s_waitcnt lgkmcnt(10)
; DEV u16 f2bf(float f) { return (u16)(pack2(f, 0.f) & 0xffffu); }
;     ...
;         float4 v = *(float4*)(sC + r * 128 + c4);
;         v.x *= rinv; v.y *= rinv; v.z *= rinv; v.w *= rinv;
;         *(float4*)(sC + r * 128 + c4) = v;
;       }
;       __syncthreads();
;       if (EPI == EPI_Q) {
;         u16* out = (u16*)(p.ws + zz + O_QB);
;         const float* AXC = (const float*)(p.ws + zz + O_AXC); const float* AXS = (const float*)(p.ws + zz + O_AXS);
;         for (int i = tid; i < 128 * 128; i += NTHR) {
;           int r = i >> 7, c = i & 127;
;           int row = m0 + r, col = n0 + c;
;           float v = sC[r * 128 + c];
;           int hc = col % 96;
;           if (row < T_LAT && hc >= 64) {
;             int d = hc - 64; int sub = d >> 4, dd = d & 15, f = dd & 7; bool first = dd < 8;
;             int t = row & 2047;
;             int pos = sub == 0 ? (t >> 6) : (t & 63);
;             float cs = AXC[pos * 8 + f], sn = AXS[pos * 8 + f];
;             float other = sC[r * 128 + (first ? c + 8 : c - 8)];
;             v = first ? (v * cs - other * sn) : (other * sn + v * cs);
;           }
;           out[(size_t)row * 384 + col] = f2bf(v);
	v_pk_mul_f32 v[44:45], v[44:45], v[178:179] op_sel_hi:[1,0]
	v_pk_mul_f32 v[46:47], v[46:47], v[178:179] op_sel_hi:[1,0]
	ds_write_b128 v102, v[44:47] offset:12288
	ds_read_b128 v[76:79], v102 offset:45056
	s_waitcnt lgkmcnt(11)
	v_pk_mul_f32 v[48:49], v[48:49], v[180:181] op_sel_hi:[1,0]
	v_pk_mul_f32 v[50:51], v[50:51], v[180:181] op_sel_hi:[1,0]
	ds_write_b128 v102, v[48:51] offset:16384
	ds_read_b128 v[80:83], v102 offset:49152
	s_waitcnt lgkmcnt(12)
	v_pk_mul_f32 v[52:53], v[52:53], v[182:183] op_sel_hi:[1,0]
	v_pk_mul_f32 v[54:55], v[54:55], v[182:183] op_sel_hi:[1,0]
	ds_write_b128 v102, v[52:55] offset:20480
	ds_read_b128 v[84:87], v102 offset:53248
	s_waitcnt lgkmcnt(13)
	v_pk_mul_f32 v[56:57], v[56:57], v[184:185] op_sel_hi:[1,0]
	v_pk_mul_f32 v[58:59], v[58:59], v[184:185] op_sel_hi:[1,0]
	ds_write_b128 v102, v[56:59] offset:24576
	ds_read_b128 v[88:91], v102 offset:57344
	s_waitcnt lgkmcnt(14)
	v_pk_mul_f32 v[60:61], v[60:61], v[186:187] op_sel_hi:[1,0]
	v_pk_mul_f32 v[62:63], v[62:63], v[186:187] op_sel_hi:[1,0]
	ds_write_b128 v102, v[60:63] offset:28672
	ds_read_b128 v[92:95], v102 offset:61440
	s_waitcnt lgkmcnt(14)
	v_pk_mul_f32 v[64:65], v[64:65], v[188:189] op_sel_hi:[1,0]
	v_pk_mul_f32 v[66:67], v[66:67], v[188:189] op_sel_hi:[1,0]
	ds_write_b128 v102, v[64:67] offset:32768
	s_waitcnt lgkmcnt(13)
	v_pk_mul_f32 v[68:69], v[68:69], v[190:191] op_sel_hi:[1,0]
	v_pk_mul_f32 v[70:71], v[70:71], v[190:191] op_sel_hi:[1,0]
	ds_write_b128 v102, v[68:71] offset:36864
	s_waitcnt lgkmcnt(12)
	v_pk_mul_f32 v[72:73], v[72:73], v[192:193] op_sel_hi:[1,0]
	v_pk_mul_f32 v[74:75], v[74:75], v[192:193] op_sel_hi:[1,0]
	ds_write_b128 v102, v[72:75] offset:40960
	s_waitcnt lgkmcnt(11)
	v_pk_mul_f32 v[76:77], v[76:77], v[194:195] op_sel_hi:[1,0]
	v_pk_mul_f32 v[78:79], v[78:79], v[194:195] op_sel_hi:[1,0]
	ds_write_b128 v102, v[76:79] offset:45056
	s_waitcnt lgkmcnt(10)
	v_pk_mul_f32 v[80:81], v[80:81], v[196:197] op_sel_hi:[1,0]
	v_pk_mul_f32 v[82:83], v[82:83], v[196:197] op_sel_hi:[1,0]
	ds_write_b128 v102, v[80:83] offset:49152
	s_waitcnt lgkmcnt(9)
	v_pk_mul_f32 v[84:85], v[84:85], v[198:199] op_sel_hi:[1,0]
	v_pk_mul_f32 v[86:87], v[86:87], v[198:199] op_sel_hi:[1,0]
	ds_write_b128 v102, v[84:87] offset:53248
	s_waitcnt lgkmcnt(8)
	v_pk_mul_f32 v[88:89], v[88:89], v[200:201] op_sel_hi:[1,0]
	v_pk_mul_f32 v[90:91], v[90:91], v[200:201] op_sel_hi:[1,0]
	ds_write_b128 v102, v[88:91] offset:57344
	s_waitcnt lgkmcnt(7)
	v_pk_mul_f32 v[92:93], v[92:93], v[202:203] op_sel_hi:[1,0]
	v_pk_mul_f32 v[94:95], v[94:95], v[202:203] op_sel_hi:[1,0]
	ds_write_b128 v102, v[92:95] offset:61440
.LBB0_1382:
	s_or_b64 exec, exec, s[0:1]
	s_waitcnt lgkmcnt(0)
	s_barrier
	s_and_saveexec_b64 s[0:1], s[6:7]
	s_cbranch_execz .LBB0_1374
	v_and_b32_e32 v0, 15, v124
	v_lshlrev_b32_e32 v0, 3, v0
	v_lshrrev_b32_e32 v1, 4, v124
	v_or_b32_e32 v2, s8, v0
	s_mov_b32 s9, 0x2aaaaaab
	v_mul_hi_i32 v3, v2, s9
	v_lshrrev_b32_e32 v4, 31, v3
	v_lshrrev_b32_e32 v3, 4, v3
	v_add_u32_e32 v3, v3, v4
	s_movk_i32 s9, 0x60
	v_mul_lo_u32 v3, v3, s9
	v_sub_u32_e32 v3, v2, v3
	v_lshlrev_b32_e32 v5, 9, v1
	v_lshl_or_b32 v5, v0, 2, v5
	v_and_b32_e32 v4, 8, v3
	v_cmp_eq_u32_e64 s[10:11], 0, v4
	v_cmp_lt_i32_e64 s[12:13], 63, v3
	s_cmp_lt_i32 s38, s48
	s_cselect_b64 s[40:41], -1, 0
	s_nop 3
	s_and_b64 s[12:13], s[12:13], s[40:41]
	v_mov_b32_e32 v6, 32
	v_mov_b32_e32 v4, 0xffffffe0
	v_cndmask_b32_e64 v6, v4, v6, s[10:11]
	v_add_u32_e32 v6, v5, v6
	v_and_b32_e32 v4, 16, v3
	v_cmp_eq_u32_e64 s[40:41], 0, v4
	v_add_u32_e32 v7, s38, v1
	v_mul_u32_u24_e32 v44, 0x300, v7
	v_lshl_add_u32 v44, v2, 1, v44
	ds_read_b128 v[8:11], v5 offset:0
	ds_read_b128 v[12:15], v5 offset:16
	s_and_saveexec_b64 s[22:23], s[12:13]
	s_cbranch_execz .Lq2_nr0
	ds_read_b128 v[16:19], v6 offset:0
	ds_read_b128 v[20:23], v6 offset:16
	v_and_b32_e32 v24, 0x7ff, v7
	v_lshrrev_b32_e32 v25, 6, v24
	v_and_b32_e32 v24, 63, v24
	v_cndmask_b32_e64 v24, v24, v25, s[40:41]
	v_lshlrev_b32_e32 v24, 5, v24
	global_load_dwordx4 v[28:31], v24, s[18:19]
	global_load_dwordx4 v[32:35], v24, s[18:19] offset:16
	global_load_dwordx4 v[36:39], v24, s[20:21]
	global_load_dwordx4 v[40:43], v24, s[20:21] offset:16
	s_waitcnt vmcnt(0) lgkmcnt(0)
	v_mul_f32_e32 v25, v36, v16
	v_cndmask_b32_e64 v25, v25, -v25, s[10:11]
	v_fmac_f32_e32 v25, v8, v28
	v_mov_b32_e32 v8, v25
	v_mul_f32_e32 v25, v37, v17
	v_cndmask_b32_e64 v25, v25, -v25, s[10:11]
	v_fmac_f32_e32 v25, v9, v29
	v_mov_b32_e32 v9, v25
	v_mul_f32_e32 v25, v38, v18
	v_cndmask_b32_e64 v25, v25, -v25, s[10:11]
	v_fmac_f32_e32 v25, v10, v30
	v_mov_b32_e32 v10, v25
	v_mul_f32_e32 v25, v39, v19
	v_cndmask_b32_e64 v25, v25, -v25, s[10:11]
	v_fmac_f32_e32 v25, v11, v31
	v_mov_b32_e32 v11, v25
	v_mul_f32_e32 v25, v40, v20
	v_cndmask_b32_e64 v25, v25, -v25, s[10:11]
	v_fmac_f32_e32 v25, v12, v32
	v_mov_b32_e32 v12, v25
	v_mul_f32_e32 v25, v41, v21
	v_cndmask_b32_e64 v25, v25, -v25, s[10:11]
	v_fmac_f32_e32 v25, v13, v33
	v_mov_b32_e32 v13, v25
	v_mul_f32_e32 v25, v42, v22
	v_cndmask_b32_e64 v25, v25, -v25, s[10:11]
	v_fmac_f32_e32 v25, v14, v34
	v_mov_b32_e32 v14, v25
	v_mul_f32_e32 v25, v43, v23
	v_cndmask_b32_e64 v25, v25, -v25, s[10:11]
	v_fmac_f32_e32 v25, v15, v35
	v_mov_b32_e32 v15, v25
; DEV u16 f2bf(float f) { return (u16)(pack2(f, 0.f) & 0xffffu); }
;     ...
;         for (int i = tid; i < 128 * 128; i += NTHR) {
;           int r = i >> 7, c = i & 127;
;           int row = m0 + r, col = n0 + c;
;           float v = sC[r * 128 + c];
;           int hc = col % 96;
;           if (row < T_LAT && hc >= 64) {
;             int d = hc - 64; int sub = d >> 4, dd = d & 15, f = dd & 7; bool first = dd < 8;
;             int t = row & 2047;
;             int pos = sub == 0 ? (t >> 6) : (t & 63);
;             float cs = AXC[pos * 8 + f], sn = AXS[pos * 8 + f];
;             float other = sC[r * 128 + (first ? c + 8 : c - 8)];
;             v = first ? (v * cs - other * sn) : (other * sn + v * cs);
;           }
;           out[(size_t)row * 384 + col] = f2bf(v);
.Lq2_nr0:
	s_or_b64 exec, exec, s[22:23]
	s_waitcnt lgkmcnt(0)
	v_cvt_pk_bf16_f32 v8, v8, v9
	v_cvt_pk_bf16_f32 v9, v10, v11
	v_cvt_pk_bf16_f32 v10, v12, v13
	v_cvt_pk_bf16_f32 v11, v14, v15
	global_store_dwordx4 v44, v[8:11], s[16:17]
	v_add_u32_e32 v44, 0x3000, v44
	v_add_u32_e32 v7, 16, v7
	ds_read_b128 v[8:11], v5 offset:8192
	ds_read_b128 v[12:15], v5 offset:8208
	s_and_saveexec_b64 s[22:23], s[12:13]
	s_cbranch_execz .Lq2_nr1
	ds_read_b128 v[16:19], v6 offset:8192
	ds_read_b128 v[20:23], v6 offset:8208
	v_and_b32_e32 v24, 0x7ff, v7
	v_lshrrev_b32_e32 v25, 6, v24
	v_and_b32_e32 v24, 63, v24
	v_cndmask_b32_e64 v24, v24, v25, s[40:41]
	v_lshlrev_b32_e32 v24, 5, v24
	global_load_dwordx4 v[28:31], v24, s[18:19]
	global_load_dwordx4 v[32:35], v24, s[18:19] offset:16
	global_load_dwordx4 v[36:39], v24, s[20:21]
	global_load_dwordx4 v[40:43], v24, s[20:21] offset:16
	s_waitcnt vmcnt(0) lgkmcnt(0)
	v_mul_f32_e32 v25, v36, v16
	v_cndmask_b32_e64 v25, v25, -v25, s[10:11]
	v_fmac_f32_e32 v25, v8, v28
	v_mov_b32_e32 v8, v25
	v_mul_f32_e32 v25, v37, v17
	v_cndmask_b32_e64 v25, v25, -v25, s[10:11]
	v_fmac_f32_e32 v25, v9, v29
	v_mov_b32_e32 v9, v25
	v_mul_f32_e32 v25, v38, v18
	v_cndmask_b32_e64 v25, v25, -v25, s[10:11]
	v_fmac_f32_e32 v25, v10, v30
	v_mov_b32_e32 v10, v25
	v_mul_f32_e32 v25, v39, v19
	v_cndmask_b32_e64 v25, v25, -v25, s[10:11]
	v_fmac_f32_e32 v25, v11, v31
	v_mov_b32_e32 v11, v25
	v_mul_f32_e32 v25, v40, v20
	v_cndmask_b32_e64 v25, v25, -v25, s[10:11]
	v_fmac_f32_e32 v25, v12, v32
	v_mov_b32_e32 v12, v25
	v_mul_f32_e32 v25, v41, v21
	v_cndmask_b32_e64 v25, v25, -v25, s[10:11]
	v_fmac_f32_e32 v25, v13, v33
	v_mov_b32_e32 v13, v25
	v_mul_f32_e32 v25, v42, v22
	v_cndmask_b32_e64 v25, v25, -v25, s[10:11]
	v_fmac_f32_e32 v25, v14, v34
	v_mov_b32_e32 v14, v25
	v_mul_f32_e32 v25, v43, v23
	v_cndmask_b32_e64 v25, v25, -v25, s[10:11]
	v_fmac_f32_e32 v25, v15, v35
	v_mov_b32_e32 v15, v25
.Lq2_nr1:
	s_or_b64 exec, exec, s[22:23]
	s_waitcnt lgkmcnt(0)
	v_cvt_pk_bf16_f32 v8, v8, v9
	v_cvt_pk_bf16_f32 v9, v10, v11
	v_cvt_pk_bf16_f32 v10, v12, v13
	v_cvt_pk_bf16_f32 v11, v14, v15
	global_store_dwordx4 v44, v[8:11], s[16:17]
	v_add_u32_e32 v44, 0x3000, v44
	v_add_u32_e32 v7, 16, v7
	ds_read_b128 v[8:11], v5 offset:16384
	ds_read_b128 v[12:15], v5 offset:16400
	s_and_saveexec_b64 s[22:23], s[12:13]
	s_cbranch_execz .Lq2_nr2
	ds_read_b128 v[16:19], v6 offset:16384
	ds_read_b128 v[20:23], v6 offset:16400
	v_and_b32_e32 v24, 0x7ff, v7
	v_lshrrev_b32_e32 v25, 6, v24
	v_and_b32_e32 v24, 63, v24
	v_cndmask_b32_e64 v24, v24, v25, s[40:41]
	v_lshlrev_b32_e32 v24, 5, v24
	global_load_dwordx4 v[28:31], v24, s[18:19]
	global_load_dwordx4 v[32:35], v24, s[18:19] offset:16
	global_load_dwordx4 v[36:39], v24, s[20:21]
	global_load_dwordx4 v[40:43], v24, s[20:21] offset:16
	s_waitcnt vmcnt(0) lgkmcnt(0)
	v_mul_f32_e32 v25, v36, v16
	v_cndmask_b32_e64 v25, v25, -v25, s[10:11]
	v_fmac_f32_e32 v25, v8, v28
	v_mov_b32_e32 v8, v25
	v_mul_f32_e32 v25, v37, v17
	v_cndmask_b32_e64 v25, v25, -v25, s[10:11]
	v_fmac_f32_e32 v25, v9, v29
	v_mov_b32_e32 v9, v25
	v_mul_f32_e32 v25, v38, v18
	v_cndmask_b32_e64 v25, v25, -v25, s[10:11]
	v_fmac_f32_e32 v25, v10, v30
	v_mov_b32_e32 v10, v25
	v_mul_f32_e32 v25, v39, v19
	v_cndmask_b32_e64 v25, v25, -v25, s[10:11]
	v_fmac_f32_e32 v25, v11, v31
	v_mov_b32_e32 v11, v25
	v_mul_f32_e32 v25, v40, v20
	v_cndmask_b32_e64 v25, v25, -v25, s[10:11]
	v_fmac_f32_e32 v25, v12, v32
	v_mov_b32_e32 v12, v25
	v_mul_f32_e32 v25, v41, v21
	v_cndmask_b32_e64 v25, v25, -v25, s[10:11]
	v_fmac_f32_e32 v25, v13, v33
	v_mov_b32_e32 v13, v25
	v_mul_f32_e32 v25, v42, v22
	v_cndmask_b32_e64 v25, v25, -v25, s[10:11]
	v_fmac_f32_e32 v25, v14, v34
	v_mov_b32_e32 v14, v25
	v_mul_f32_e32 v25, v43, v23
	v_cndmask_b32_e64 v25, v25, -v25, s[10:11]
	v_fmac_f32_e32 v25, v15, v35
	v_mov_b32_e32 v15, v25
.Lq2_nr2:
	s_or_b64 exec, exec, s[22:23]
	s_waitcnt lgkmcnt(0)
	v_cvt_pk_bf16_f32 v8, v8, v9
	v_cvt_pk_bf16_f32 v9, v10, v11
	v_cvt_pk_bf16_f32 v10, v12, v13
	v_cvt_pk_bf16_f32 v11, v14, v15
	global_store_dwordx4 v44, v[8:11], s[16:17]
	v_add_u32_e32 v44, 0x3000, v44
	v_add_u32_e32 v7, 16, v7
	ds_read_b128 v[8:11], v5 offset:24576
	ds_read_b128 v[12:15], v5 offset:24592
	s_and_saveexec_b64 s[22:23], s[12:13]
	s_cbranch_execz .Lq2_nr3
	ds_read_b128 v[16:19], v6 offset:24576
	ds_read_b128 v[20:23], v6 offset:24592
	v_and_b32_e32 v24, 0x7ff, v7
	v_lshrrev_b32_e32 v25, 6, v24
	v_and_b32_e32 v24, 63, v24
	v_cndmask_b32_e64 v24, v24, v25, s[40:41]
	v_lshlrev_b32_e32 v24, 5, v24
	global_load_dwordx4 v[28:31], v24, s[18:19]
	global_load_dwordx4 v[32:35], v24, s[18:19] offset:16
	global_load_dwordx4 v[36:39], v24, s[20:21]
	global_load_dwordx4 v[40:43], v24, s[20:21] offset:16
	s_waitcnt vmcnt(0) lgkmcnt(0)
	v_mul_f32_e32 v25, v36, v16
	v_cndmask_b32_e64 v25, v25, -v25, s[10:11]
	v_fmac_f32_e32 v25, v8, v28
	v_mov_b32_e32 v8, v25
	v_mul_f32_e32 v25, v37, v17
	v_cndmask_b32_e64 v25, v25, -v25, s[10:11]
	v_fmac_f32_e32 v25, v9, v29
	v_mov_b32_e32 v9, v25
	v_mul_f32_e32 v25, v38, v18
	v_cndmask_b32_e64 v25, v25, -v25, s[10:11]
	v_fmac_f32_e32 v25, v10, v30
	v_mov_b32_e32 v10, v25
	v_mul_f32_e32 v25, v39, v19
	v_cndmask_b32_e64 v25, v25, -v25, s[10:11]
	v_fmac_f32_e32 v25, v11, v31
	v_mov_b32_e32 v11, v25
	v_mul_f32_e32 v25, v40, v20
	v_cndmask_b32_e64 v25, v25, -v25, s[10:11]
	v_fmac_f32_e32 v25, v12, v32
	v_mov_b32_e32 v12, v25
	v_mul_f32_e32 v25, v41, v21
	v_cndmask_b32_e64 v25, v25, -v25, s[10:11]
	v_fmac_f32_e32 v25, v13, v33
	v_mov_b32_e32 v13, v25
	v_mul_f32_e32 v25, v42, v22
	v_cndmask_b32_e64 v25, v25, -v25, s[10:11]
	v_fmac_f32_e32 v25, v14, v34
	v_mov_b32_e32 v14, v25
	v_mul_f32_e32 v25, v43, v23
	v_cndmask_b32_e64 v25, v25, -v25, s[10:11]
	v_fmac_f32_e32 v25, v15, v35
	v_mov_b32_e32 v15, v25
; DEV u16 f2bf(float f) { return (u16)(pack2(f, 0.f) & 0xffffu); }
;     ...
;         for (int i = tid; i < 128 * 128; i += NTHR) {
;           int r = i >> 7, c = i & 127;
;           int row = m0 + r, col = n0 + c;
;           float v = sC[r * 128 + c];
;           int hc = col % 96;
;           if (row < T_LAT && hc >= 64) {
;             int d = hc - 64; int sub = d >> 4, dd = d & 15, f = dd & 7; bool first = dd < 8;
;             int t = row & 2047;
;             int pos = sub == 0 ? (t >> 6) : (t & 63);
;             float cs = AXC[pos * 8 + f], sn = AXS[pos * 8 + f];
;             float other = sC[r * 128 + (first ? c + 8 : c - 8)];
;             v = first ? (v * cs - other * sn) : (other * sn + v * cs);
;           }
;           out[(size_t)row * 384 + col] = f2bf(v);
.Lq2_nr3:
	s_or_b64 exec, exec, s[22:23]
	s_waitcnt lgkmcnt(0)
	v_cvt_pk_bf16_f32 v8, v8, v9
	v_cvt_pk_bf16_f32 v9, v10, v11
	v_cvt_pk_bf16_f32 v10, v12, v13
	v_cvt_pk_bf16_f32 v11, v14, v15
	global_store_dwordx4 v44, v[8:11], s[16:17]
	v_add_u32_e32 v44, 0x3000, v44
	v_add_u32_e32 v7, 16, v7
	ds_read_b128 v[8:11], v5 offset:32768
	ds_read_b128 v[12:15], v5 offset:32784
	s_and_saveexec_b64 s[22:23], s[12:13]
	s_cbranch_execz .Lq2_nr4
	ds_read_b128 v[16:19], v6 offset:32768
	ds_read_b128 v[20:23], v6 offset:32784
	v_and_b32_e32 v24, 0x7ff, v7
	v_lshrrev_b32_e32 v25, 6, v24
	v_and_b32_e32 v24, 63, v24
	v_cndmask_b32_e64 v24, v24, v25, s[40:41]
	v_lshlrev_b32_e32 v24, 5, v24
	global_load_dwordx4 v[28:31], v24, s[18:19]
	global_load_dwordx4 v[32:35], v24, s[18:19] offset:16
	global_load_dwordx4 v[36:39], v24, s[20:21]
	global_load_dwordx4 v[40:43], v24, s[20:21] offset:16
	s_waitcnt vmcnt(0) lgkmcnt(0)
	v_mul_f32_e32 v25, v36, v16
	v_cndmask_b32_e64 v25, v25, -v25, s[10:11]
	v_fmac_f32_e32 v25, v8, v28
	v_mov_b32_e32 v8, v25
	v_mul_f32_e32 v25, v37, v17
	v_cndmask_b32_e64 v25, v25, -v25, s[10:11]
	v_fmac_f32_e32 v25, v9, v29
	v_mov_b32_e32 v9, v25
	v_mul_f32_e32 v25, v38, v18
	v_cndmask_b32_e64 v25, v25, -v25, s[10:11]
	v_fmac_f32_e32 v25, v10, v30
	v_mov_b32_e32 v10, v25
	v_mul_f32_e32 v25, v39, v19
	v_cndmask_b32_e64 v25, v25, -v25, s[10:11]
	v_fmac_f32_e32 v25, v11, v31
	v_mov_b32_e32 v11, v25
	v_mul_f32_e32 v25, v40, v20
	v_cndmask_b32_e64 v25, v25, -v25, s[10:11]
	v_fmac_f32_e32 v25, v12, v32
	v_mov_b32_e32 v12, v25
	v_mul_f32_e32 v25, v41, v21
	v_cndmask_b32_e64 v25, v25, -v25, s[10:11]
	v_fmac_f32_e32 v25, v13, v33
	v_mov_b32_e32 v13, v25
	v_mul_f32_e32 v25, v42, v22
	v_cndmask_b32_e64 v25, v25, -v25, s[10:11]
	v_fmac_f32_e32 v25, v14, v34
	v_mov_b32_e32 v14, v25
	v_mul_f32_e32 v25, v43, v23
	v_cndmask_b32_e64 v25, v25, -v25, s[10:11]
	v_fmac_f32_e32 v25, v15, v35
	v_mov_b32_e32 v15, v25
.Lq2_nr4:
	s_or_b64 exec, exec, s[22:23]
	s_waitcnt lgkmcnt(0)
	v_cvt_pk_bf16_f32 v8, v8, v9
	v_cvt_pk_bf16_f32 v9, v10, v11
	v_cvt_pk_bf16_f32 v10, v12, v13
	v_cvt_pk_bf16_f32 v11, v14, v15
	global_store_dwordx4 v44, v[8:11], s[16:17]
	v_add_u32_e32 v44, 0x3000, v44
	v_add_u32_e32 v7, 16, v7
	ds_read_b128 v[8:11], v5 offset:40960
	ds_read_b128 v[12:15], v5 offset:40976
	s_and_saveexec_b64 s[22:23], s[12:13]
	s_cbranch_execz .Lq2_nr5
	ds_read_b128 v[16:19], v6 offset:40960
	ds_read_b128 v[20:23], v6 offset:40976
	v_and_b32_e32 v24, 0x7ff, v7
	v_lshrrev_b32_e32 v25, 6, v24
	v_and_b32_e32 v24, 63, v24
	v_cndmask_b32_e64 v24, v24, v25, s[40:41]
	v_lshlrev_b32_e32 v24, 5, v24
	global_load_dwordx4 v[28:31], v24, s[18:19]
	global_load_dwordx4 v[32:35], v24, s[18:19] offset:16
	global_load_dwordx4 v[36:39], v24, s[20:21]
	global_load_dwordx4 v[40:43], v24, s[20:21] offset:16
	s_waitcnt vmcnt(0) lgkmcnt(0)
	v_mul_f32_e32 v25, v36, v16
	v_cndmask_b32_e64 v25, v25, -v25, s[10:11]
	v_fmac_f32_e32 v25, v8, v28
	v_mov_b32_e32 v8, v25
	v_mul_f32_e32 v25, v37, v17
	v_cndmask_b32_e64 v25, v25, -v25, s[10:11]
	v_fmac_f32_e32 v25, v9, v29
	v_mov_b32_e32 v9, v25
	v_mul_f32_e32 v25, v38, v18
	v_cndmask_b32_e64 v25, v25, -v25, s[10:11]
	v_fmac_f32_e32 v25, v10, v30
	v_mov_b32_e32 v10, v25
	v_mul_f32_e32 v25, v39, v19
	v_cndmask_b32_e64 v25, v25, -v25, s[10:11]
	v_fmac_f32_e32 v25, v11, v31
	v_mov_b32_e32 v11, v25
	v_mul_f32_e32 v25, v40, v20
	v_cndmask_b32_e64 v25, v25, -v25, s[10:11]
	v_fmac_f32_e32 v25, v12, v32
	v_mov_b32_e32 v12, v25
	v_mul_f32_e32 v25, v41, v21
	v_cndmask_b32_e64 v25, v25, -v25, s[10:11]
	v_fmac_f32_e32 v25, v13, v33
	v_mov_b32_e32 v13, v25
	v_mul_f32_e32 v25, v42, v22
	v_cndmask_b32_e64 v25, v25, -v25, s[10:11]
	v_fmac_f32_e32 v25, v14, v34
	v_mov_b32_e32 v14, v25
	v_mul_f32_e32 v25, v43, v23
	v_cndmask_b32_e64 v25, v25, -v25, s[10:11]
	v_fmac_f32_e32 v25, v15, v35
	v_mov_b32_e32 v15, v25
; DEV u16 f2bf(float f) { return (u16)(pack2(f, 0.f) & 0xffffu); }
;     ...
;         for (int i = tid; i < 128 * 128; i += NTHR) {
;           int r = i >> 7, c = i & 127;
;           int row = m0 + r, col = n0 + c;
;           float v = sC[r * 128 + c];
;           int hc = col % 96;
;           if (row < T_LAT && hc >= 64) {
;             int d = hc - 64; int sub = d >> 4, dd = d & 15, f = dd & 7; bool first = dd < 8;
;             int t = row & 2047;
;             int pos = sub == 0 ? (t >> 6) : (t & 63);
;             float cs = AXC[pos * 8 + f], sn = AXS[pos * 8 + f];
;             float other = sC[r * 128 + (first ? c + 8 : c - 8)];
;             v = first ? (v * cs - other * sn) : (other * sn + v * cs);
;           }
;           out[(size_t)row * 384 + col] = f2bf(v);
.Lq2_nr5:
	s_or_b64 exec, exec, s[22:23]
	s_waitcnt lgkmcnt(0)
	v_cvt_pk_bf16_f32 v8, v8, v9
	v_cvt_pk_bf16_f32 v9, v10, v11
	v_cvt_pk_bf16_f32 v10, v12, v13
	v_cvt_pk_bf16_f32 v11, v14, v15
	global_store_dwordx4 v44, v[8:11], s[16:17]
	v_add_u32_e32 v44, 0x3000, v44
	v_add_u32_e32 v7, 16, v7
	ds_read_b128 v[8:11], v5 offset:49152
	ds_read_b128 v[12:15], v5 offset:49168
	s_and_saveexec_b64 s[22:23], s[12:13]
	s_cbranch_execz .Lq2_nr6
	ds_read_b128 v[16:19], v6 offset:49152
	ds_read_b128 v[20:23], v6 offset:49168
	v_and_b32_e32 v24, 0x7ff, v7
	v_lshrrev_b32_e32 v25, 6, v24
	v_and_b32_e32 v24, 63, v24
	v_cndmask_b32_e64 v24, v24, v25, s[40:41]
	v_lshlrev_b32_e32 v24, 5, v24
	global_load_dwordx4 v[28:31], v24, s[18:19]
	global_load_dwordx4 v[32:35], v24, s[18:19] offset:16
	global_load_dwordx4 v[36:39], v24, s[20:21]
	global_load_dwordx4 v[40:43], v24, s[20:21] offset:16
	s_waitcnt vmcnt(0) lgkmcnt(0)
	v_mul_f32_e32 v25, v36, v16
	v_cndmask_b32_e64 v25, v25, -v25, s[10:11]
	v_fmac_f32_e32 v25, v8, v28
	v_mov_b32_e32 v8, v25
	v_mul_f32_e32 v25, v37, v17
	v_cndmask_b32_e64 v25, v25, -v25, s[10:11]
	v_fmac_f32_e32 v25, v9, v29
	v_mov_b32_e32 v9, v25
	v_mul_f32_e32 v25, v38, v18
	v_cndmask_b32_e64 v25, v25, -v25, s[10:11]
	v_fmac_f32_e32 v25, v10, v30
	v_mov_b32_e32 v10, v25
	v_mul_f32_e32 v25, v39, v19
	v_cndmask_b32_e64 v25, v25, -v25, s[10:11]
	v_fmac_f32_e32 v25, v11, v31
	v_mov_b32_e32 v11, v25
	v_mul_f32_e32 v25, v40, v20
	v_cndmask_b32_e64 v25, v25, -v25, s[10:11]
	v_fmac_f32_e32 v25, v12, v32
	v_mov_b32_e32 v12, v25
	v_mul_f32_e32 v25, v41, v21
	v_cndmask_b32_e64 v25, v25, -v25, s[10:11]
	v_fmac_f32_e32 v25, v13, v33
	v_mov_b32_e32 v13, v25
	v_mul_f32_e32 v25, v42, v22
	v_cndmask_b32_e64 v25, v25, -v25, s[10:11]
	v_fmac_f32_e32 v25, v14, v34
	v_mov_b32_e32 v14, v25
	v_mul_f32_e32 v25, v43, v23
	v_cndmask_b32_e64 v25, v25, -v25, s[10:11]
	v_fmac_f32_e32 v25, v15, v35
	v_mov_b32_e32 v15, v25
.Lq2_nr6:
	s_or_b64 exec, exec, s[22:23]
	s_waitcnt lgkmcnt(0)
	v_cvt_pk_bf16_f32 v8, v8, v9
	v_cvt_pk_bf16_f32 v9, v10, v11
	v_cvt_pk_bf16_f32 v10, v12, v13
	v_cvt_pk_bf16_f32 v11, v14, v15
	global_store_dwordx4 v44, v[8:11], s[16:17]
	v_add_u32_e32 v44, 0x3000, v44
	v_add_u32_e32 v7, 16, v7
	ds_read_b128 v[8:11], v5 offset:57344
	ds_read_b128 v[12:15], v5 offset:57360
	s_and_saveexec_b64 s[22:23], s[12:13]
	s_cbranch_execz .Lq2_nr7
	ds_read_b128 v[16:19], v6 offset:57344
	ds_read_b128 v[20:23], v6 offset:57360
	v_and_b32_e32 v24, 0x7ff, v7
	v_lshrrev_b32_e32 v25, 6, v24
	v_and_b32_e32 v24, 63, v24
	v_cndmask_b32_e64 v24, v24, v25, s[40:41]
	v_lshlrev_b32_e32 v24, 5, v24
	global_load_dwordx4 v[28:31], v24, s[18:19]
	global_load_dwordx4 v[32:35], v24, s[18:19] offset:16
	global_load_dwordx4 v[36:39], v24, s[20:21]
	global_load_dwordx4 v[40:43], v24, s[20:21] offset:16
	s_waitcnt vmcnt(0) lgkmcnt(0)
	v_mul_f32_e32 v25, v36, v16
	v_cndmask_b32_e64 v25, v25, -v25, s[10:11]
	v_fmac_f32_e32 v25, v8, v28
	v_mov_b32_e32 v8, v25
	v_mul_f32_e32 v25, v37, v17
	v_cndmask_b32_e64 v25, v25, -v25, s[10:11]
	v_fmac_f32_e32 v25, v9, v29
	v_mov_b32_e32 v9, v25
	v_mul_f32_e32 v25, v38, v18
	v_cndmask_b32_e64 v25, v25, -v25, s[10:11]
	v_fmac_f32_e32 v25, v10, v30
	v_mov_b32_e32 v10, v25
	v_mul_f32_e32 v25, v39, v19
	v_cndmask_b32_e64 v25, v25, -v25, s[10:11]
	v_fmac_f32_e32 v25, v11, v31
	v_mov_b32_e32 v11, v25
	v_mul_f32_e32 v25, v40, v20
	v_cndmask_b32_e64 v25, v25, -v25, s[10:11]
	v_fmac_f32_e32 v25, v12, v32
	v_mov_b32_e32 v12, v25
	v_mul_f32_e32 v25, v41, v21
	v_cndmask_b32_e64 v25, v25, -v25, s[10:11]
	v_fmac_f32_e32 v25, v13, v33
	v_mov_b32_e32 v13, v25
	v_mul_f32_e32 v25, v42, v22
	v_cndmask_b32_e64 v25, v25, -v25, s[10:11]
	v_fmac_f32_e32 v25, v14, v34
	v_mov_b32_e32 v14, v25
	v_mul_f32_e32 v25, v43, v23
	v_cndmask_b32_e64 v25, v25, -v25, s[10:11]
	v_fmac_f32_e32 v25, v15, v35
	v_mov_b32_e32 v15, v25
.Lq2_nr7:
	s_or_b64 exec, exec, s[22:23]
	s_waitcnt lgkmcnt(0)
	v_cvt_pk_bf16_f32 v8, v8, v9
	v_cvt_pk_bf16_f32 v9, v10, v11
	v_cvt_pk_bf16_f32 v10, v12, v13
	v_cvt_pk_bf16_f32 v11, v14, v15
	global_store_dwordx4 v44, v[8:11], s[16:17]
	s_branch .LBB0_1374

; DEV float lo2f(u32 w) { return __uint_as_float(w << 16); }
; DEV float hi2f(u32 w) { return __uint_as_float(w & 0xffff0000u); }
; template <int HOOK>
; __device__ __forceinline__ void gemm_tile(const u16* __restrict__ A, int lda, const u16* __restrict__ B, int ldb, int K, char* smem, const float* ssq = nullptr) {
;     ...
;   __syncthreads();
;   float* sC = (float*)smem;
; #pragma unroll
;   for (int i = 0; i < 4; i++)
; #pragma unroll
;     for (int j = 0; j < 4; j++)
; #pragma unroll
;       for (int r = 0; r < 4; r++) sC[(wm + i * 16 + lq * 4 + r) * 128 + wn + j * 16 + lr] = acc[i][j][r];
;   __syncthreads();
;     ...
;       for (int i = tid; i < 128 * 32; i += NTHR) {
;         int r = i >> 5, sub = i & 31, c4 = sub * 4;
;         int row = m0 + r;
;         float ss = 0.f;
;         if (EPI == EPI_Q) {
;           uint4 w = *(const uint4*)(Pm + (size_t)row * LDP + sub * 8);
;           float a;
;           a = lo2f(w.x); ss += a * a; a = hi2f(w.x); ss += a * a; a = lo2f(w.y); ss += a * a; a = hi2f(w.y); ss += a * a;
;           a = lo2f(w.z); ss += a * a; a = hi2f(w.z); ss += a * a; a = lo2f(w.w); ss += a * a; a = hi2f(w.w); ss += a * a;
;         } else {
;           uint2 w = *(const uint2*)(Pm + (size_t)row * LDP + 256 + sub * 4);
;           float a;
;           a = lo2f(w.x); ss += a * a; a = hi2f(w.x); ss += a * a; a = lo2f(w.y); ss += a * a; a = hi2f(w.y); ss += a * a;
;         }
;         ss += __shfl_xor(ss, 1, 64); ss += __shfl_xor(ss, 2, 64); ss += __shfl_xor(ss, 4, 64);
;         ss += __shfl_xor(ss, 8, 64); ss += __shfl_xor(ss, 16, 64);
.LBB0_1395:
	s_waitcnt vmcnt(7)
	v_lshlrev_b32_e32 v1, 9, v125
	v_and_or_b32 v0, v123, 64, v124
	v_lshl_or_b32 v1, v126, 11, v1
	v_lshl_or_b32 v0, v0, 2, v1
	v_add_u32_e32 v1, 0x400, v0
	s_barrier
	ds_write2_b32 v0, v92, v88 offset1:16
	ds_write2_b32 v0, v93, v89 offset0:128 offset1:144
	ds_write2_b32 v1, v94, v90 offset1:16
	ds_write2_b32 v1, v95, v91 offset0:128 offset1:144
	ds_write2_b32 v0, v84, v80 offset0:32 offset1:48
	ds_write2_b32 v0, v85, v81 offset0:160 offset1:176
	ds_write2_b32 v1, v86, v82 offset0:32 offset1:48
	ds_write2_b32 v1, v87, v83 offset0:160 offset1:176
	v_add_u32_e32 v1, 0x2000, v0
	v_add_u32_e32 v2, 0x2400, v0
	ds_write2_b32 v1, v76, v72 offset1:16
	ds_write2_b32 v1, v77, v73 offset0:128 offset1:144
	ds_write2_b32 v2, v78, v74 offset1:16
	ds_write2_b32 v2, v79, v75 offset0:128 offset1:144
	ds_write2_b32 v1, v68, v64 offset0:32 offset1:48
	ds_write2_b32 v1, v69, v65 offset0:160 offset1:176
	ds_write2_b32 v2, v70, v66 offset0:32 offset1:48
	ds_write2_b32 v2, v71, v67 offset0:160 offset1:176
	v_add_u32_e32 v1, 0x4000, v0
	v_add_u32_e32 v2, 0x4400, v0
	ds_write2_b32 v1, v60, v56 offset1:16
	ds_write2_b32 v1, v61, v57 offset0:128 offset1:144
	ds_write2_b32 v2, v62, v58 offset1:16
	ds_write2_b32 v2, v63, v59 offset0:128 offset1:144
	ds_write2_b32 v1, v52, v48 offset0:32 offset1:48
	ds_write2_b32 v1, v53, v49 offset0:160 offset1:176
	ds_write2_b32 v2, v54, v50 offset0:32 offset1:48
	ds_write2_b32 v2, v55, v51 offset0:160 offset1:176
	v_add_u32_e32 v1, 0x6000, v0
	v_add_u32_e32 v0, 0x6400, v0
	ds_write2_b32 v1, v44, v40 offset1:16
	ds_write2_b32 v1, v45, v41 offset0:128 offset1:144
	ds_write2_b32 v0, v46, v42 offset1:16
	ds_write2_b32 v0, v47, v43 offset0:128 offset1:144
	ds_write2_b32 v1, v36, v32 offset0:32 offset1:48
	ds_write2_b32 v1, v37, v33 offset0:160 offset1:176
	ds_write2_b32 v0, v38, v34 offset0:32 offset1:48
	ds_write2_b32 v0, v39, v35 offset0:160 offset1:176
	s_waitcnt lgkmcnt(0)
	s_barrier
	s_and_saveexec_b64 s[0:1], s[4:5]
	s_mov_b32 s29, 0x800000
	s_movk_i32 s36, 0xeff
	s_movk_i32 s37, 0x1800
	s_cbranch_execz .LBB0_1398
	v_and_b32_e32 v1, 64, v212
	v_xor_b32_e32 v0, 1, v212
	s_waitcnt vmcnt(6)
	v_add_u32_e32 v4, 64, v1
	v_cmp_lt_i32_e32 vcc, v0, v4
	v_xor_b32_e32 v1, 2, v212
	v_xor_b32_e32 v2, 4, v212
	v_cndmask_b32_e32 v0, v212, v0, vcc
	v_cmp_lt_i32_e32 vcc, v1, v4
	v_xor_b32_e32 v3, 8, v212
	v_xor_b32_e32 v5, 16, v212
	v_cndmask_b32_e32 v1, v212, v1, vcc
	v_cmp_lt_i32_e32 vcc, v2, v4
	v_lshlrev_b32_e32 v0, 2, v0
	v_lshlrev_b32_e32 v1, 2, v1
	v_cndmask_b32_e32 v2, v212, v2, vcc
	v_cmp_lt_i32_e32 vcc, v3, v4
	v_lshlrev_b32_e32 v2, 2, v2
	s_mov_b64 s[12:13], 0
	v_cndmask_b32_e32 v3, v212, v3, vcc
	v_cmp_lt_i32_e32 vcc, v5, v4
	v_lshlrev_b32_e32 v3, 2, v3
	v_mov_b32_e32 v6, v120
	v_cndmask_b32_e32 v4, v212, v5, vcc
	v_lshlrev_b32_e32 v4, 2, v4
	v_mov_b32_e32 v5, v121
	v_lshrrev_b32_e32 v14, 5, v120
	v_and_b32_e32 v15, 31, v120
	v_lshlrev_b32_e32 v102, 4, v15
	v_lshl_or_b32 v102, v14, 9, v102
	v_add_u32_e32 v14, s28, v14
	v_lshlrev_b32_e32 v100, 3, v15
	v_mov_b32_e32 v101, 0
	v_lshl_add_u64 v[100:101], s[8:9], 0, v[100:101]
	v_add_co_u32_e32 v100, vcc, 0x15319000, v100
	s_nop 1
	v_addc_co_u32_e32 v101, vcc, 0, v101, vcc
	v_mad_i64_i32 v[6:7], s[34:35], v14, s37, v[100:101]
	global_load_dwordx2 v[32:33], v[6:7], off offset:512
	v_add_u32_e32 v14, 8, v14
	v_mad_i64_i32 v[6:7], s[34:35], v14, s37, v[100:101]
	global_load_dwordx2 v[36:37], v[6:7], off offset:512
	v_add_u32_e32 v14, 8, v14
	v_mad_i64_i32 v[6:7], s[34:35], v14, s37, v[100:101]
	global_load_dwordx2 v[40:41], v[6:7], off offset:512
	v_add_u32_e32 v14, 8, v14
	v_mad_i64_i32 v[6:7], s[34:35], v14, s37, v[100:101]
	global_load_dwordx2 v[44:45], v[6:7], off offset:512
	v_add_u32_e32 v14, 8, v14
	v_mad_i64_i32 v[6:7], s[34:35], v14, s37, v[100:101]
	global_load_dwordx2 v[48:49], v[6:7], off offset:512
	v_add_u32_e32 v14, 8, v14
	v_mad_i64_i32 v[6:7], s[34:35], v14, s37, v[100:101]
	global_load_dwordx2 v[52:53], v[6:7], off offset:512
	v_add_u32_e32 v14, 8, v14
	v_mad_i64_i32 v[6:7], s[34:35], v14, s37, v[100:101]
	global_load_dwordx2 v[56:57], v[6:7], off offset:512
	v_add_u32_e32 v14, 8, v14
	v_mad_i64_i32 v[6:7], s[34:35], v14, s37, v[100:101]
	global_load_dwordx2 v[60:61], v[6:7], off offset:512
	v_add_u32_e32 v14, 8, v14
	v_mad_i64_i32 v[6:7], s[34:35], v14, s37, v[100:101]
	global_load_dwordx2 v[64:65], v[6:7], off offset:512
	v_add_u32_e32 v14, 8, v14
	v_mad_i64_i32 v[6:7], s[34:35], v14, s37, v[100:101]
	global_load_dwordx2 v[68:69], v[6:7], off offset:512
	v_add_u32_e32 v14, 8, v14
	v_mad_i64_i32 v[6:7], s[34:35], v14, s37, v[100:101]
	global_load_dwordx2 v[72:73], v[6:7], off offset:512
	v_add_u32_e32 v14, 8, v14
	v_mad_i64_i32 v[6:7], s[34:35], v14, s37, v[100:101]
	global_load_dwordx2 v[76:77], v[6:7], off offset:512
	v_add_u32_e32 v14, 8, v14
	v_mad_i64_i32 v[6:7], s[34:35], v14, s37, v[100:101]
	global_load_dwordx2 v[80:81], v[6:7], off offset:512
	v_add_u32_e32 v14, 8, v14
	v_mad_i64_i32 v[6:7], s[34:35], v14, s37, v[100:101]
	global_load_dwordx2 v[84:85], v[6:7], off offset:512
	v_add_u32_e32 v14, 8, v14
	v_mad_i64_i32 v[6:7], s[34:35], v14, s37, v[100:101]
	global_load_dwordx2 v[88:89], v[6:7], off offset:512
	v_add_u32_e32 v14, 8, v14
	v_mad_i64_i32 v[6:7], s[34:35], v14, s37, v[100:101]
	global_load_dwordx2 v[92:93], v[6:7], off offset:512
	s_waitcnt vmcnt(15)
	v_lshlrev_b32_e32 v10, 16, v32
	v_and_b32_e32 v11, 0xffff0000, v32
	v_lshlrev_b32_e32 v13, 16, v33
	v_and_b32_e32 v12, 0xffff0000, v33
	v_pk_mul_f32 v[8:9], v[10:11], v[10:11]
	v_pk_mul_f32 v[10:11], v[12:13], v[12:13]
	v_add_f32_e32 v8, v8, v9
	v_add_f32_e32 v8, v8, v11
	v_add_f32_e32 v172, v10, v8
	s_waitcnt vmcnt(14)
; DEV float lo2f(u32 w) { return __uint_as_float(w << 16); }
; DEV float hi2f(u32 w) { return __uint_as_float(w & 0xffff0000u); }
;     ...
;         } else {
;           uint2 w = *(const uint2*)(Pm + (size_t)row * LDP + 256 + sub * 4);
;           float a;
;           a = lo2f(w.x); ss += a * a; a = hi2f(w.x); ss += a * a; a = lo2f(w.y); ss += a * a; a = hi2f(w.y); ss += a * a;
;         }
	v_lshlrev_b32_e32 v10, 16, v36
	v_and_b32_e32 v11, 0xffff0000, v36
	v_lshlrev_b32_e32 v13, 16, v37
	v_and_b32_e32 v12, 0xffff0000, v37
	v_pk_mul_f32 v[8:9], v[10:11], v[10:11]
	v_pk_mul_f32 v[10:11], v[12:13], v[12:13]
	v_add_f32_e32 v8, v8, v9
	v_add_f32_e32 v8, v8, v11
	v_add_f32_e32 v174, v10, v8
	s_waitcnt vmcnt(13)
	v_lshlrev_b32_e32 v10, 16, v40
	v_and_b32_e32 v11, 0xffff0000, v40
	v_lshlrev_b32_e32 v13, 16, v41
	v_and_b32_e32 v12, 0xffff0000, v41
	v_pk_mul_f32 v[8:9], v[10:11], v[10:11]
	v_pk_mul_f32 v[10:11], v[12:13], v[12:13]
	v_add_f32_e32 v8, v8, v9
	v_add_f32_e32 v8, v8, v11
	v_add_f32_e32 v176, v10, v8
	s_waitcnt vmcnt(12)
	v_lshlrev_b32_e32 v10, 16, v44
	v_and_b32_e32 v11, 0xffff0000, v44
	v_lshlrev_b32_e32 v13, 16, v45
	v_and_b32_e32 v12, 0xffff0000, v45
	v_pk_mul_f32 v[8:9], v[10:11], v[10:11]
	v_pk_mul_f32 v[10:11], v[12:13], v[12:13]
	v_add_f32_e32 v8, v8, v9
	v_add_f32_e32 v8, v8, v11
	v_add_f32_e32 v178, v10, v8
	s_waitcnt vmcnt(11)
	v_lshlrev_b32_e32 v10, 16, v48
	v_and_b32_e32 v11, 0xffff0000, v48
	v_lshlrev_b32_e32 v13, 16, v49
	v_and_b32_e32 v12, 0xffff0000, v49
	v_pk_mul_f32 v[8:9], v[10:11], v[10:11]
	v_pk_mul_f32 v[10:11], v[12:13], v[12:13]
	v_add_f32_e32 v8, v8, v9
	v_add_f32_e32 v8, v8, v11
	v_add_f32_e32 v180, v10, v8
	s_waitcnt vmcnt(10)
	v_lshlrev_b32_e32 v10, 16, v52
	v_and_b32_e32 v11, 0xffff0000, v52
	v_lshlrev_b32_e32 v13, 16, v53
	v_and_b32_e32 v12, 0xffff0000, v53
	v_pk_mul_f32 v[8:9], v[10:11], v[10:11]
	v_pk_mul_f32 v[10:11], v[12:13], v[12:13]
	v_add_f32_e32 v8, v8, v9
	v_add_f32_e32 v8, v8, v11
	v_add_f32_e32 v182, v10, v8
	s_waitcnt vmcnt(9)
	v_lshlrev_b32_e32 v10, 16, v56
	v_and_b32_e32 v11, 0xffff0000, v56
	v_lshlrev_b32_e32 v13, 16, v57
	v_and_b32_e32 v12, 0xffff0000, v57
	v_pk_mul_f32 v[8:9], v[10:11], v[10:11]
	v_pk_mul_f32 v[10:11], v[12:13], v[12:13]
	v_add_f32_e32 v8, v8, v9
	v_add_f32_e32 v8, v8, v11
	v_add_f32_e32 v184, v10, v8
	s_waitcnt vmcnt(8)
	v_lshlrev_b32_e32 v10, 16, v60
	v_and_b32_e32 v11, 0xffff0000, v60
	v_lshlrev_b32_e32 v13, 16, v61
	v_and_b32_e32 v12, 0xffff0000, v61
	v_pk_mul_f32 v[8:9], v[10:11], v[10:11]
	v_pk_mul_f32 v[10:11], v[12:13], v[12:13]
	v_add_f32_e32 v8, v8, v9
	v_add_f32_e32 v8, v8, v11
	v_add_f32_e32 v186, v10, v8
	s_waitcnt vmcnt(7)
	v_lshlrev_b32_e32 v10, 16, v64
	v_and_b32_e32 v11, 0xffff0000, v64
	v_lshlrev_b32_e32 v13, 16, v65
	v_and_b32_e32 v12, 0xffff0000, v65
	v_pk_mul_f32 v[8:9], v[10:11], v[10:11]
	v_pk_mul_f32 v[10:11], v[12:13], v[12:13]
	v_add_f32_e32 v8, v8, v9
	v_add_f32_e32 v8, v8, v11
	v_add_f32_e32 v188, v10, v8
	s_waitcnt vmcnt(6)
	v_lshlrev_b32_e32 v10, 16, v68
	v_and_b32_e32 v11, 0xffff0000, v68
	v_lshlrev_b32_e32 v13, 16, v69
	v_and_b32_e32 v12, 0xffff0000, v69
	v_pk_mul_f32 v[8:9], v[10:11], v[10:11]
	v_pk_mul_f32 v[10:11], v[12:13], v[12:13]
	v_add_f32_e32 v8, v8, v9
	v_add_f32_e32 v8, v8, v11
	v_add_f32_e32 v190, v10, v8
	s_waitcnt vmcnt(5)
	v_lshlrev_b32_e32 v10, 16, v72
	v_and_b32_e32 v11, 0xffff0000, v72
	v_lshlrev_b32_e32 v13, 16, v73
	v_and_b32_e32 v12, 0xffff0000, v73
	v_pk_mul_f32 v[8:9], v[10:11], v[10:11]
	v_pk_mul_f32 v[10:11], v[12:13], v[12:13]
	v_add_f32_e32 v8, v8, v9
	v_add_f32_e32 v8, v8, v11
	v_add_f32_e32 v192, v10, v8
	s_waitcnt vmcnt(4)
	v_lshlrev_b32_e32 v10, 16, v76
	v_and_b32_e32 v11, 0xffff0000, v76
	v_lshlrev_b32_e32 v13, 16, v77
	v_and_b32_e32 v12, 0xffff0000, v77
	v_pk_mul_f32 v[8:9], v[10:11], v[10:11]
	v_pk_mul_f32 v[10:11], v[12:13], v[12:13]
	v_add_f32_e32 v8, v8, v9
	v_add_f32_e32 v8, v8, v11
	v_add_f32_e32 v194, v10, v8
	s_waitcnt vmcnt(3)
	v_lshlrev_b32_e32 v10, 16, v80
	v_and_b32_e32 v11, 0xffff0000, v80
	v_lshlrev_b32_e32 v13, 16, v81
	v_and_b32_e32 v12, 0xffff0000, v81
	v_pk_mul_f32 v[8:9], v[10:11], v[10:11]
	v_pk_mul_f32 v[10:11], v[12:13], v[12:13]
	v_add_f32_e32 v8, v8, v9
	v_add_f32_e32 v8, v8, v11
	v_add_f32_e32 v196, v10, v8
	s_waitcnt vmcnt(2)
	v_lshlrev_b32_e32 v10, 16, v84
	v_and_b32_e32 v11, 0xffff0000, v84
	v_lshlrev_b32_e32 v13, 16, v85
	v_and_b32_e32 v12, 0xffff0000, v85
	v_pk_mul_f32 v[8:9], v[10:11], v[10:11]
	v_pk_mul_f32 v[10:11], v[12:13], v[12:13]
	v_add_f32_e32 v8, v8, v9
	v_add_f32_e32 v8, v8, v11
	v_add_f32_e32 v198, v10, v8
	s_waitcnt vmcnt(1)
	v_lshlrev_b32_e32 v10, 16, v88
	v_and_b32_e32 v11, 0xffff0000, v88
	v_lshlrev_b32_e32 v13, 16, v89
	v_and_b32_e32 v12, 0xffff0000, v89
	v_pk_mul_f32 v[8:9], v[10:11], v[10:11]
	v_pk_mul_f32 v[10:11], v[12:13], v[12:13]
	v_add_f32_e32 v8, v8, v9
	v_add_f32_e32 v8, v8, v11
	v_add_f32_e32 v200, v10, v8
	s_waitcnt vmcnt(0)
	v_lshlrev_b32_e32 v10, 16, v92
	v_and_b32_e32 v11, 0xffff0000, v92
	v_lshlrev_b32_e32 v13, 16, v93
	v_and_b32_e32 v12, 0xffff0000, v93
	v_pk_mul_f32 v[8:9], v[10:11], v[10:11]
	v_pk_mul_f32 v[10:11], v[12:13], v[12:13]
	v_add_f32_e32 v8, v8, v9
	v_add_f32_e32 v8, v8, v11
	v_add_f32_e32 v202, v10, v8
	ds_bpermute_b32 v173, v0, v172
	ds_bpermute_b32 v175, v0, v174
	ds_bpermute_b32 v177, v0, v176
	ds_bpermute_b32 v179, v0, v178
	ds_bpermute_b32 v181, v0, v180
	ds_bpermute_b32 v183, v0, v182
	ds_bpermute_b32 v185, v0, v184
	ds_bpermute_b32 v187, v0, v186
	s_waitcnt lgkmcnt(7)
	v_add_f32_e32 v172, v172, v173
	ds_bpermute_b32 v189, v0, v188
	s_waitcnt lgkmcnt(7)
	v_add_f32_e32 v174, v174, v175
	ds_bpermute_b32 v191, v0, v190
	s_waitcnt lgkmcnt(7)
	v_add_f32_e32 v176, v176, v177
	ds_bpermute_b32 v193, v0, v192
	s_waitcnt lgkmcnt(7)
	v_add_f32_e32 v178, v178, v179
	ds_bpermute_b32 v195, v0, v194
	s_waitcnt lgkmcnt(7)
	v_add_f32_e32 v180, v180, v181
	ds_bpermute_b32 v197, v0, v196
	s_waitcnt lgkmcnt(7)
	v_add_f32_e32 v182, v182, v183
	ds_bpermute_b32 v199, v0, v198
	s_waitcnt lgkmcnt(7)
;     ...
;         ss += __shfl_xor(ss, 1, 64); ss += __shfl_xor(ss, 2, 64); ss += __shfl_xor(ss, 4, 64);
;         ss += __shfl_xor(ss, 8, 64); ss += __shfl_xor(ss, 16, 64);
	v_add_f32_e32 v184, v184, v185
	ds_bpermute_b32 v201, v0, v200
	s_waitcnt lgkmcnt(7)
	v_add_f32_e32 v186, v186, v187
	ds_bpermute_b32 v203, v0, v202
	s_waitcnt lgkmcnt(7)
	v_add_f32_e32 v188, v188, v189
	s_waitcnt lgkmcnt(6)
	v_add_f32_e32 v190, v190, v191
	s_waitcnt lgkmcnt(5)
	v_add_f32_e32 v192, v192, v193
	s_waitcnt lgkmcnt(4)
	v_add_f32_e32 v194, v194, v195
	s_waitcnt lgkmcnt(3)
	v_add_f32_e32 v196, v196, v197
	s_waitcnt lgkmcnt(2)
	v_add_f32_e32 v198, v198, v199
	s_waitcnt lgkmcnt(1)
	v_add_f32_e32 v200, v200, v201
	s_waitcnt lgkmcnt(0)
	v_add_f32_e32 v202, v202, v203
	ds_bpermute_b32 v173, v1, v172
	ds_bpermute_b32 v175, v1, v174
	ds_bpermute_b32 v177, v1, v176
	ds_bpermute_b32 v179, v1, v178
	ds_bpermute_b32 v181, v1, v180
	ds_bpermute_b32 v183, v1, v182
	ds_bpermute_b32 v185, v1, v184
	ds_bpermute_b32 v187, v1, v186
	s_waitcnt lgkmcnt(7)
	v_add_f32_e32 v172, v172, v173
	ds_bpermute_b32 v189, v1, v188
	s_waitcnt lgkmcnt(7)
	v_add_f32_e32 v174, v174, v175
	ds_bpermute_b32 v191, v1, v190
	s_waitcnt lgkmcnt(7)
	v_add_f32_e32 v176, v176, v177
	ds_bpermute_b32 v193, v1, v192
	s_waitcnt lgkmcnt(7)
	v_add_f32_e32 v178, v178, v179
	ds_bpermute_b32 v195, v1, v194
	s_waitcnt lgkmcnt(7)
	v_add_f32_e32 v180, v180, v181
	ds_bpermute_b32 v197, v1, v196
	s_waitcnt lgkmcnt(7)
	v_add_f32_e32 v182, v182, v183
	ds_bpermute_b32 v199, v1, v198
	s_waitcnt lgkmcnt(7)
	v_add_f32_e32 v184, v184, v185
	ds_bpermute_b32 v201, v1, v200
	s_waitcnt lgkmcnt(7)
	v_add_f32_e32 v186, v186, v187
	ds_bpermute_b32 v203, v1, v202
	s_waitcnt lgkmcnt(7)
	v_add_f32_e32 v188, v188, v189
	s_waitcnt lgkmcnt(6)
	v_add_f32_e32 v190, v190, v191
	s_waitcnt lgkmcnt(5)
	v_add_f32_e32 v192, v192, v193
	s_waitcnt lgkmcnt(4)
	v_add_f32_e32 v194, v194, v195
	s_waitcnt lgkmcnt(3)
	v_add_f32_e32 v196, v196, v197
	s_waitcnt lgkmcnt(2)
	v_add_f32_e32 v198, v198, v199
	s_waitcnt lgkmcnt(1)
	v_add_f32_e32 v200, v200, v201
	s_waitcnt lgkmcnt(0)
	v_add_f32_e32 v202, v202, v203
	ds_bpermute_b32 v173, v2, v172
	ds_bpermute_b32 v175, v2, v174
	ds_bpermute_b32 v177, v2, v176
	ds_bpermute_b32 v179, v2, v178
	ds_bpermute_b32 v181, v2, v180
	ds_bpermute_b32 v183, v2, v182
	ds_bpermute_b32 v185, v2, v184
	ds_bpermute_b32 v187, v2, v186
	s_waitcnt lgkmcnt(7)
	v_add_f32_e32 v172, v172, v173
	ds_bpermute_b32 v189, v2, v188
	s_waitcnt lgkmcnt(7)
	v_add_f32_e32 v174, v174, v175
	ds_bpermute_b32 v191, v2, v190
	s_waitcnt lgkmcnt(7)
	v_add_f32_e32 v176, v176, v177
	ds_bpermute_b32 v193, v2, v192
	s_waitcnt lgkmcnt(7)
	v_add_f32_e32 v178, v178, v179
	ds_bpermute_b32 v195, v2, v194
	s_waitcnt lgkmcnt(7)
	v_add_f32_e32 v180, v180, v181
	ds_bpermute_b32 v197, v2, v196
	s_waitcnt lgkmcnt(7)
	v_add_f32_e32 v182, v182, v183
	ds_bpermute_b32 v199, v2, v198
	s_waitcnt lgkmcnt(7)
	v_add_f32_e32 v184, v184, v185
	ds_bpermute_b32 v201, v2, v200
	s_waitcnt lgkmcnt(7)
	v_add_f32_e32 v186, v186, v187
	ds_bpermute_b32 v203, v2, v202
	s_waitcnt lgkmcnt(7)
	v_add_f32_e32 v188, v188, v189
	s_waitcnt lgkmcnt(6)
	v_add_f32_e32 v190, v190, v191
	s_waitcnt lgkmcnt(5)
	v_add_f32_e32 v192, v192, v193
	s_waitcnt lgkmcnt(4)
	v_add_f32_e32 v194, v194, v195
	s_waitcnt lgkmcnt(3)
	v_add_f32_e32 v196, v196, v197
	s_waitcnt lgkmcnt(2)
	v_add_f32_e32 v198, v198, v199
	s_waitcnt lgkmcnt(1)
	v_add_f32_e32 v200, v200, v201
	s_waitcnt lgkmcnt(0)
	v_add_f32_e32 v202, v202, v203
	ds_bpermute_b32 v173, v3, v172
	ds_bpermute_b32 v175, v3, v174
	ds_bpermute_b32 v177, v3, v176
	ds_bpermute_b32 v179, v3, v178
	ds_bpermute_b32 v181, v3, v180
	ds_bpermute_b32 v183, v3, v182
	ds_bpermute_b32 v185, v3, v184
	ds_bpermute_b32 v187, v3, v186
	s_waitcnt lgkmcnt(7)
	v_add_f32_e32 v172, v172, v173
	ds_bpermute_b32 v189, v3, v188
	s_waitcnt lgkmcnt(7)
	v_add_f32_e32 v174, v174, v175
	ds_bpermute_b32 v191, v3, v190
	s_waitcnt lgkmcnt(7)
	v_add_f32_e32 v176, v176, v177
	ds_bpermute_b32 v193, v3, v192
	s_waitcnt lgkmcnt(7)
	v_add_f32_e32 v178, v178, v179
	ds_bpermute_b32 v195, v3, v194
	s_waitcnt lgkmcnt(7)
	v_add_f32_e32 v180, v180, v181
	ds_bpermute_b32 v197, v3, v196
	s_waitcnt lgkmcnt(7)
	v_add_f32_e32 v182, v182, v183
	ds_bpermute_b32 v199, v3, v198
	s_waitcnt lgkmcnt(7)
	v_add_f32_e32 v184, v184, v185
	ds_bpermute_b32 v201, v3, v200
	s_waitcnt lgkmcnt(7)
	v_add_f32_e32 v186, v186, v187
	ds_bpermute_b32 v203, v3, v202
	s_waitcnt lgkmcnt(7)
	v_add_f32_e32 v188, v188, v189
	s_waitcnt lgkmcnt(6)
	v_add_f32_e32 v190, v190, v191
	s_waitcnt lgkmcnt(5)
	v_add_f32_e32 v192, v192, v193
	s_waitcnt lgkmcnt(4)
	v_add_f32_e32 v194, v194, v195
	s_waitcnt lgkmcnt(3)
	v_add_f32_e32 v196, v196, v197
	s_waitcnt lgkmcnt(2)
	v_add_f32_e32 v198, v198, v199
	s_waitcnt lgkmcnt(1)
	v_add_f32_e32 v200, v200, v201
	s_waitcnt lgkmcnt(0)
	v_add_f32_e32 v202, v202, v203
	ds_bpermute_b32 v173, v4, v172
	ds_bpermute_b32 v175, v4, v174
	ds_bpermute_b32 v177, v4, v176
	ds_bpermute_b32 v179, v4, v178
	ds_bpermute_b32 v181, v4, v180
	ds_bpermute_b32 v183, v4, v182
	ds_bpermute_b32 v185, v4, v184
	ds_bpermute_b32 v187, v4, v186
	s_waitcnt lgkmcnt(7)
	v_add_f32_e32 v172, v172, v173
	ds_bpermute_b32 v189, v4, v188
	s_waitcnt lgkmcnt(7)
	v_add_f32_e32 v174, v174, v175
	ds_bpermute_b32 v191, v4, v190
	s_waitcnt lgkmcnt(7)
	v_add_f32_e32 v176, v176, v177
	ds_bpermute_b32 v193, v4, v192
	s_waitcnt lgkmcnt(7)
	v_add_f32_e32 v178, v178, v179
	ds_bpermute_b32 v195, v4, v194
	s_waitcnt lgkmcnt(7)
	v_add_f32_e32 v180, v180, v181
	ds_bpermute_b32 v197, v4, v196
	s_waitcnt lgkmcnt(7)
	v_add_f32_e32 v182, v182, v183
	ds_bpermute_b32 v199, v4, v198
	s_waitcnt lgkmcnt(7)
	v_add_f32_e32 v184, v184, v185
	ds_bpermute_b32 v201, v4, v200
	s_waitcnt lgkmcnt(7)
	v_add_f32_e32 v186, v186, v187
	ds_bpermute_b32 v203, v4, v202
	s_waitcnt lgkmcnt(7)
;     ...
;         ss += __shfl_xor(ss, 1, 64); ss += __shfl_xor(ss, 2, 64); ss += __shfl_xor(ss, 4, 64);
;         ss += __shfl_xor(ss, 8, 64); ss += __shfl_xor(ss, 16, 64);
;         float rinv = (EPI == EPI_Q) ? rsqrtf(ss * (1.f / 256.f) + 1e-6f) * (0.10206207261596577f * 1.4426950408889634f)
;                                     : rsqrtf(ss * (1.f / 128.f) + 1e-6f);
;         float4 v = *(float4*)(sC + r * 128 + c4);
;         v.x *= rinv; v.y *= rinv; v.z *= rinv; v.w *= rinv;
;         *(float4*)(sC + r * 128 + c4) = v;
	v_add_f32_e32 v188, v188, v189
	s_waitcnt lgkmcnt(6)
	v_add_f32_e32 v190, v190, v191
	s_waitcnt lgkmcnt(5)
	v_add_f32_e32 v192, v192, v193
	s_waitcnt lgkmcnt(4)
	v_add_f32_e32 v194, v194, v195
	s_waitcnt lgkmcnt(3)
	v_add_f32_e32 v196, v196, v197
	s_waitcnt lgkmcnt(2)
	v_add_f32_e32 v198, v198, v199
	s_waitcnt lgkmcnt(1)
	v_add_f32_e32 v200, v200, v201
	s_waitcnt lgkmcnt(0)
	v_add_f32_e32 v202, v202, v203
	v_fmamk_f32 v6, v172, 0x3c000000, v211
	v_mul_f32_e32 v8, 0x4b800000, v6
	v_cmp_gt_f32_e32 vcc, s29, v6
	s_nop 1
	v_cndmask_b32_e32 v6, v6, v8, vcc
	v_rsq_f32_e32 v13, v6
	s_nop 0
	v_mul_f32_e32 v12, 0x45800000, v13
	v_cndmask_b32_e32 v172, v13, v12, vcc
	v_fmamk_f32 v6, v174, 0x3c000000, v211
	v_mul_f32_e32 v8, 0x4b800000, v6
	v_cmp_gt_f32_e32 vcc, s29, v6
	s_nop 1
	v_cndmask_b32_e32 v6, v6, v8, vcc
	v_rsq_f32_e32 v13, v6
	s_nop 0
	v_mul_f32_e32 v12, 0x45800000, v13
	v_cndmask_b32_e32 v174, v13, v12, vcc
	v_fmamk_f32 v6, v176, 0x3c000000, v211
	v_mul_f32_e32 v8, 0x4b800000, v6
	v_cmp_gt_f32_e32 vcc, s29, v6
	s_nop 1
	v_cndmask_b32_e32 v6, v6, v8, vcc
	v_rsq_f32_e32 v13, v6
	s_nop 0
	v_mul_f32_e32 v12, 0x45800000, v13
	v_cndmask_b32_e32 v176, v13, v12, vcc
	v_fmamk_f32 v6, v178, 0x3c000000, v211
	v_mul_f32_e32 v8, 0x4b800000, v6
	v_cmp_gt_f32_e32 vcc, s29, v6
	s_nop 1
	v_cndmask_b32_e32 v6, v6, v8, vcc
	v_rsq_f32_e32 v13, v6
	s_nop 0
	v_mul_f32_e32 v12, 0x45800000, v13
	v_cndmask_b32_e32 v178, v13, v12, vcc
	v_fmamk_f32 v6, v180, 0x3c000000, v211
	v_mul_f32_e32 v8, 0x4b800000, v6
	v_cmp_gt_f32_e32 vcc, s29, v6
	s_nop 1
	v_cndmask_b32_e32 v6, v6, v8, vcc
	v_rsq_f32_e32 v13, v6
	s_nop 0
	v_mul_f32_e32 v12, 0x45800000, v13
	v_cndmask_b32_e32 v180, v13, v12, vcc
	v_fmamk_f32 v6, v182, 0x3c000000, v211
	v_mul_f32_e32 v8, 0x4b800000, v6
	v_cmp_gt_f32_e32 vcc, s29, v6
	s_nop 1
	v_cndmask_b32_e32 v6, v6, v8, vcc
	v_rsq_f32_e32 v13, v6
	s_nop 0
	v_mul_f32_e32 v12, 0x45800000, v13
	v_cndmask_b32_e32 v182, v13, v12, vcc
	v_fmamk_f32 v6, v184, 0x3c000000, v211
	v_mul_f32_e32 v8, 0x4b800000, v6
	v_cmp_gt_f32_e32 vcc, s29, v6
	s_nop 1
	v_cndmask_b32_e32 v6, v6, v8, vcc
	v_rsq_f32_e32 v13, v6
	s_nop 0
	v_mul_f32_e32 v12, 0x45800000, v13
	v_cndmask_b32_e32 v184, v13, v12, vcc
	v_fmamk_f32 v6, v186, 0x3c000000, v211
	v_mul_f32_e32 v8, 0x4b800000, v6
	v_cmp_gt_f32_e32 vcc, s29, v6
	s_nop 1
	v_cndmask_b32_e32 v6, v6, v8, vcc
	v_rsq_f32_e32 v13, v6
	s_nop 0
	v_mul_f32_e32 v12, 0x45800000, v13
	v_cndmask_b32_e32 v186, v13, v12, vcc
	v_fmamk_f32 v6, v188, 0x3c000000, v211
	v_mul_f32_e32 v8, 0x4b800000, v6
	v_cmp_gt_f32_e32 vcc, s29, v6
	s_nop 1
	v_cndmask_b32_e32 v6, v6, v8, vcc
	v_rsq_f32_e32 v13, v6
	s_nop 0
	v_mul_f32_e32 v12, 0x45800000, v13
	v_cndmask_b32_e32 v188, v13, v12, vcc
	v_fmamk_f32 v6, v190, 0x3c000000, v211
	v_mul_f32_e32 v8, 0x4b800000, v6
	v_cmp_gt_f32_e32 vcc, s29, v6
	s_nop 1
	v_cndmask_b32_e32 v6, v6, v8, vcc
	v_rsq_f32_e32 v13, v6
	s_nop 0
	v_mul_f32_e32 v12, 0x45800000, v13
	v_cndmask_b32_e32 v190, v13, v12, vcc
	v_fmamk_f32 v6, v192, 0x3c000000, v211
	v_mul_f32_e32 v8, 0x4b800000, v6
	v_cmp_gt_f32_e32 vcc, s29, v6
	s_nop 1
	v_cndmask_b32_e32 v6, v6, v8, vcc
	v_rsq_f32_e32 v13, v6
	s_nop 0
	v_mul_f32_e32 v12, 0x45800000, v13
	v_cndmask_b32_e32 v192, v13, v12, vcc
	v_fmamk_f32 v6, v194, 0x3c000000, v211
	v_mul_f32_e32 v8, 0x4b800000, v6
	v_cmp_gt_f32_e32 vcc, s29, v6
	s_nop 1
	v_cndmask_b32_e32 v6, v6, v8, vcc
	v_rsq_f32_e32 v13, v6
	s_nop 0
	v_mul_f32_e32 v12, 0x45800000, v13
	v_cndmask_b32_e32 v194, v13, v12, vcc
	v_fmamk_f32 v6, v196, 0x3c000000, v211
	v_mul_f32_e32 v8, 0x4b800000, v6
	v_cmp_gt_f32_e32 vcc, s29, v6
	s_nop 1
	v_cndmask_b32_e32 v6, v6, v8, vcc
	v_rsq_f32_e32 v13, v6
	s_nop 0
	v_mul_f32_e32 v12, 0x45800000, v13
	v_cndmask_b32_e32 v196, v13, v12, vcc
	v_fmamk_f32 v6, v198, 0x3c000000, v211
	v_mul_f32_e32 v8, 0x4b800000, v6
	v_cmp_gt_f32_e32 vcc, s29, v6
	s_nop 1
	v_cndmask_b32_e32 v6, v6, v8, vcc
	v_rsq_f32_e32 v13, v6
	s_nop 0
	v_mul_f32_e32 v12, 0x45800000, v13
	v_cndmask_b32_e32 v198, v13, v12, vcc
	v_fmamk_f32 v6, v200, 0x3c000000, v211
	v_mul_f32_e32 v8, 0x4b800000, v6
	v_cmp_gt_f32_e32 vcc, s29, v6
	s_nop 1
	v_cndmask_b32_e32 v6, v6, v8, vcc
	v_rsq_f32_e32 v13, v6
	s_nop 0
	v_mul_f32_e32 v12, 0x45800000, v13
	v_cndmask_b32_e32 v200, v13, v12, vcc
	v_fmamk_f32 v6, v202, 0x3c000000, v211
	v_mul_f32_e32 v8, 0x4b800000, v6
	v_cmp_gt_f32_e32 vcc, s29, v6
	s_nop 1
	v_cndmask_b32_e32 v6, v6, v8, vcc
	v_rsq_f32_e32 v13, v6
	s_nop 0
	v_mul_f32_e32 v12, 0x45800000, v13
	v_cndmask_b32_e32 v202, v13, v12, vcc
	ds_read_b128 v[32:35], v102 offset:0
	ds_read_b128 v[36:39], v102 offset:4096
	ds_read_b128 v[40:43], v102 offset:8192
	ds_read_b128 v[44:47], v102 offset:12288
	ds_read_b128 v[48:51], v102 offset:16384
	ds_read_b128 v[52:55], v102 offset:20480
	ds_read_b128 v[56:59], v102 offset:24576
	ds_read_b128 v[60:63], v102 offset:28672
	s_waitcnt lgkmcnt(7)
;     ...
;         float4 v = *(float4*)(sC + r * 128 + c4);
;         v.x *= rinv; v.y *= rinv; v.z *= rinv; v.w *= rinv;
;         *(float4*)(sC + r * 128 + c4) = v;
	v_pk_mul_f32 v[32:33], v[32:33], v[172:173] op_sel_hi:[1,0]
	v_pk_mul_f32 v[34:35], v[34:35], v[172:173] op_sel_hi:[1,0]
	ds_write_b128 v102, v[32:35] offset:0
	ds_read_b128 v[64:67], v102 offset:32768
	s_waitcnt lgkmcnt(8)
	v_pk_mul_f32 v[36:37], v[36:37], v[174:175] op_sel_hi:[1,0]
	v_pk_mul_f32 v[38:39], v[38:39], v[174:175] op_sel_hi:[1,0]
	ds_write_b128 v102, v[36:39] offset:4096
	ds_read_b128 v[68:71], v102 offset:36864
	s_waitcnt lgkmcnt(9)
	v_pk_mul_f32 v[40:41], v[40:41], v[176:177] op_sel_hi:[1,0]
	v_pk_mul_f32 v[42:43], v[42:43], v[176:177] op_sel_hi:[1,0]
	ds_write_b128 v102, v[40:43] offset:8192
	ds_read_b128 v[72:75], v102 offset:40960
	s_waitcnt lgkmcnt(10)
	v_pk_mul_f32 v[44:45], v[44:45], v[178:179] op_sel_hi:[1,0]
	v_pk_mul_f32 v[46:47], v[46:47], v[178:179] op_sel_hi:[1,0]
	ds_write_b128 v102, v[44:47] offset:12288
	ds_read_b128 v[76:79], v102 offset:45056
	s_waitcnt lgkmcnt(11)
	v_pk_mul_f32 v[48:49], v[48:49], v[180:181] op_sel_hi:[1,0]
	v_pk_mul_f32 v[50:51], v[50:51], v[180:181] op_sel_hi:[1,0]
	ds_write_b128 v102, v[48:51] offset:16384
	ds_read_b128 v[80:83], v102 offset:49152
	s_waitcnt lgkmcnt(12)
	v_pk_mul_f32 v[52:53], v[52:53], v[182:183] op_sel_hi:[1,0]
	v_pk_mul_f32 v[54:55], v[54:55], v[182:183] op_sel_hi:[1,0]
	ds_write_b128 v102, v[52:55] offset:20480
	ds_read_b128 v[84:87], v102 offset:53248
	s_waitcnt lgkmcnt(13)
	v_pk_mul_f32 v[56:57], v[56:57], v[184:185] op_sel_hi:[1,0]
	v_pk_mul_f32 v[58:59], v[58:59], v[184:185] op_sel_hi:[1,0]
	ds_write_b128 v102, v[56:59] offset:24576
	ds_read_b128 v[88:91], v102 offset:57344
	s_waitcnt lgkmcnt(14)
	v_pk_mul_f32 v[60:61], v[60:61], v[186:187] op_sel_hi:[1,0]
	v_pk_mul_f32 v[62:63], v[62:63], v[186:187] op_sel_hi:[1,0]
	ds_write_b128 v102, v[60:63] offset:28672
	ds_read_b128 v[92:95], v102 offset:61440
	s_waitcnt lgkmcnt(14)
	v_pk_mul_f32 v[64:65], v[64:65], v[188:189] op_sel_hi:[1,0]
	v_pk_mul_f32 v[66:67], v[66:67], v[188:189] op_sel_hi:[1,0]
	ds_write_b128 v102, v[64:67] offset:32768
	s_waitcnt lgkmcnt(13)
	v_pk_mul_f32 v[68:69], v[68:69], v[190:191] op_sel_hi:[1,0]
	v_pk_mul_f32 v[70:71], v[70:71], v[190:191] op_sel_hi:[1,0]
	ds_write_b128 v102, v[68:71] offset:36864
	s_waitcnt lgkmcnt(12)
	v_pk_mul_f32 v[72:73], v[72:73], v[192:193] op_sel_hi:[1,0]
	v_pk_mul_f32 v[74:75], v[74:75], v[192:193] op_sel_hi:[1,0]
	ds_write_b128 v102, v[72:75] offset:40960
	s_waitcnt lgkmcnt(11)
	v_pk_mul_f32 v[76:77], v[76:77], v[194:195] op_sel_hi:[1,0]
	v_pk_mul_f32 v[78:79], v[78:79], v[194:195] op_sel_hi:[1,0]
	ds_write_b128 v102, v[76:79] offset:45056
	s_waitcnt lgkmcnt(10)
	v_pk_mul_f32 v[80:81], v[80:81], v[196:197] op_sel_hi:[1,0]
	v_pk_mul_f32 v[82:83], v[82:83], v[196:197] op_sel_hi:[1,0]
	ds_write_b128 v102, v[80:83] offset:49152
	s_waitcnt lgkmcnt(9)
	v_pk_mul_f32 v[84:85], v[84:85], v[198:199] op_sel_hi:[1,0]
	v_pk_mul_f32 v[86:87], v[86:87], v[198:199] op_sel_hi:[1,0]
	ds_write_b128 v102, v[84:87] offset:53248
	s_waitcnt lgkmcnt(8)
	v_pk_mul_f32 v[88:89], v[88:89], v[200:201] op_sel_hi:[1,0]
	v_pk_mul_f32 v[90:91], v[90:91], v[200:201] op_sel_hi:[1,0]
	ds_write_b128 v102, v[88:91] offset:57344
	s_waitcnt lgkmcnt(7)
	v_pk_mul_f32 v[92:93], v[92:93], v[202:203] op_sel_hi:[1,0]
	v_pk_mul_f32 v[94:95], v[94:95], v[202:203] op_sel_hi:[1,0]
	ds_write_b128 v102, v[92:95] offset:61440
